# GEMM loops: first K-iteration peeled with zero C operand, accumulator zeroing (128 v_mov per tile) removed
# baseline (speedup 1.0000x reference)
;     __device__ bool next(int i, Unit& u) const { if (!so.next(i >> 1, u)) return false; u.kind = i & 1; return true; }
; #define PG8_STAGE(bufoff, gbase, voff) do { _Pragma("unroll") for (int _i = 0; _i < 2; ++_i) \
;         __builtin_amdgcn_global_load_lds((const unsigned*)((const char*)(gbase) + (voff)[_i]), (LAS unsigned*)(lds + (bufoff) + ldsw + _i * 8192), 16, 0, 0); } while (0)
; #define PG8_LDA(dst, b, h) do { _Pragma("unroll") for (int m = 0; m < 4; ++m) _Pragma("unroll") for (int k = 0; k < 2; ++k) dst[m][k] = *(const LAS bf16x8*)(lds + PG8_SA(b, h) + aoff + m * 2048 + k * 1024); } while (0)
; #define PG8_LDB(dst, b, h) do { _Pragma("unroll") for (int n = 0; n < 2; ++n) _Pragma("unroll") for (int k = 0; k < 2; ++k) dst[n][k] = *(const LAS bf16x8*)(lds + PG8_SB(b, h) + boff + n * 2048 + k * 1024); } while (0)
; #define PG8_WAIT_V(n) asm volatile("s_waitcnt vmcnt(" #n ")" ::: "memory")
; #define PG8_WAIT_L(n) asm volatile("s_waitcnt lgkmcnt(" #n ")" ::: "memory")
; #define PG8_BAR __builtin_amdgcn_s_barrier()
; template <class Epi, class Sched, bool ALIGN_EPI = true, bool SP2 = true>
; __device__ __forceinline__ void gemm_phase(LAS unsigned char* lds, const Gemm g, const Sched& S, const Epi& E) {
;     ...
;         const bool has_next = S.next(ui + 1, nxt);
;         const char* nA = has_next ? (const char*)(nxt.kind ? g.A1 : g.A0) + (size_t)nxt.pm * tstep : cA; const char* nB = has_next ? (const char*)(nxt.kind ? g.B1 : g.B0) + (size_t)nxt.pn * tstep : cB;
;         for (int t = 0; t < nt; t += 2) {
;             const bool last = (t == nt - 2);
;             const char* a1 = cA + (size_t)(t + 1) * kstep;
;             const char* a2 = last ? nA : cA + (size_t)(t + 2) * kstep; const char* b2 = last ? nB : cB + (size_t)(t + 2) * kstep;
;             const char* a3 = a2 + kstep; const char* b3 = b2 + kstep;
;             if constexpr (SP2) {
;             PG8_LDB(B0, 0, 0); PG8_LDB(B1, 0, 1); PG8_SCHED; PG8_LDA(At, 0, 0); PG8_STAGE(PG8_SA(1, 1), a1 + hstep, voffA);
;             PG8_WAIT_V(8); PG8_WAIT_L(0); PG8_BAR; PG8_MMA(0, 0, At, B0); PG8_MMA(0, 1, At, B1); PG8_BAR; PG8_SCHED;
;             PG8_LDA(At, 0, 1); PG8_STAGE(PG8_SB(0, 0), b2, voffB); PG8_STAGE(PG8_SB(0, 1), b2 + hstep, voffB); PG8_STAGE(PG8_SA(0, 0), a2, voffA);
;             PG8_WAIT_V(8); PG8_WAIT_L(0); PG8_BAR; PG8_MMA(1, 0, At, B0); PG8_MMA(1, 1, At, B1); PG8_BAR; PG8_SCHED;
.LBB0_93:
	s_ashr_i32 s17, s16, 31
	s_lshl_b64 s[18:19], s[16:17], 20
	s_add_u32 s18, s88, s18
	s_addc_u32 s19, s89, s19
	s_and_b64 s[20:21], s[0:1], exec
	s_cselect_b32 s17, s19, s7
	s_cselect_b32 s56, s18, s6
	s_ashr_i32 s15, s14, 31
	s_lshl_b64 s[20:21], s[14:15], 20
	v_readlane_b32 s15, v255, 28
	s_add_u32 s20, s15, s20
	v_readlane_b32 s15, v255, 29
	s_addc_u32 s21, s15, s21
	s_and_b64 s[22:23], s[0:1], exec
	s_cselect_b32 s15, s21, s9
	s_cselect_b32 s57, s20, s8
	s_add_u32 s6, s6, 0x80080
	s_addc_u32 s7, s7, 0
	s_add_u32 s70, s8, 0x100
	s_addc_u32 s71, s9, 0
	s_mov_b32 s72, -2
	s_add_u32 s8, s6, 0xfff80080
	s_addc_u32 s9, s7, -1
	s_add_i32 s58, 0, 0x10000
	s_cmp_eq_u32 s72, 28
	s_cselect_b32 s23, s17, s9
	s_cselect_b32 s22, s56, s8
	v_add_u32_e32 v148, s58, v153
	s_cselect_b32 s9, s15, s71
	s_cselect_b32 s8, s57, s70
	s_add_i32 s73, 0, 0x14000
	ds_read_b128 v[140:143], v148
	ds_read_b128 v[144:147], v148 offset:1024
	ds_read_b128 v[160:163], v148 offset:2048
	ds_read_b128 v[164:167], v148 offset:3072
	v_add_u32_e32 v148, s73, v153
	ds_read_b128 v[168:171], v148
	ds_read_b128 v[172:175], v148 offset:1024
	ds_read_b128 v[176:179], v148 offset:2048
	ds_read_b128 v[194:197], v148 offset:3072
	v_lshl_add_u64 v[148:149], s[6:7], 0, v[136:137]
	s_add_i32 m0, s25, 0xc000
	ds_read_b128 v[198:201], v159
	ds_read_b128 v[202:205], v159 offset:1024
	ds_read_b128 v[206:209], v159 offset:2048
	ds_read_b128 v[210:213], v159 offset:3072
	ds_read_b128 v[234:237], v159 offset:4096
	ds_read_b128 v[238:241], v159 offset:5120
	ds_read_b128 v[242:245], v159 offset:6144
	ds_read_b128 v[246:249], v159 offset:7168
	global_load_lds_dwordx4 v[148:149], off
	v_lshl_add_u64 v[148:149], s[6:7], 0, v[138:139]
	s_add_i32 m0, s25, 0xe000
	s_nop 0
	global_load_lds_dwordx4 v[148:149], off
	s_waitcnt vmcnt(8)
	s_waitcnt lgkmcnt(0)
	s_barrier
	s_setprio 1
	s_waitcnt lgkmcnt(0)
	v_mfma_f32_16x16x32_bf16 v[126:129], v[140:143], v[198:201], 0
	v_mfma_f32_16x16x32_bf16 v[118:121], v[160:163], v[198:201], 0
	v_mfma_f32_16x16x32_bf16 v[110:113], v[140:143], v[206:209], 0
	v_mfma_f32_16x16x32_bf16 v[102:105], v[160:163], v[206:209], 0
	v_mfma_f32_16x16x32_bf16 v[94:97], v[140:143], v[234:237], 0
	v_mfma_f32_16x16x32_bf16 v[86:89], v[160:163], v[234:237], 0
	v_mfma_f32_16x16x32_bf16 v[78:81], v[140:143], v[242:245], 0
	v_mfma_f32_16x16x32_bf16 v[70:73], v[160:163], v[242:245], 0
	v_mfma_f32_16x16x32_bf16 v[126:129], v[144:147], v[202:205], v[126:129]
	v_mfma_f32_16x16x32_bf16 v[118:121], v[164:167], v[202:205], v[118:121]
	v_mfma_f32_16x16x32_bf16 v[110:113], v[144:147], v[210:213], v[110:113]
	v_mfma_f32_16x16x32_bf16 v[102:105], v[164:167], v[210:213], v[102:105]
	v_mfma_f32_16x16x32_bf16 v[94:97], v[144:147], v[238:241], v[94:97]
	v_mfma_f32_16x16x32_bf16 v[86:89], v[164:167], v[238:241], v[86:89]
	v_mfma_f32_16x16x32_bf16 v[78:81], v[144:147], v[246:249], v[78:81]
	v_mfma_f32_16x16x32_bf16 v[70:73], v[164:167], v[246:249], v[70:73]
	s_setprio 0
	s_setprio 1
	v_mfma_f32_16x16x32_bf16 v[122:125], v[168:171], v[198:201], 0
	v_mfma_f32_16x16x32_bf16 v[114:117], v[176:179], v[198:201], 0
	v_mfma_f32_16x16x32_bf16 v[106:109], v[168:171], v[206:209], 0
	v_mfma_f32_16x16x32_bf16 v[98:101], v[176:179], v[206:209], 0
	v_mfma_f32_16x16x32_bf16 v[90:93], v[168:171], v[234:237], 0
	v_mfma_f32_16x16x32_bf16 v[82:85], v[176:179], v[234:237], 0
	v_mfma_f32_16x16x32_bf16 v[74:77], v[168:171], v[242:245], 0
	v_mfma_f32_16x16x32_bf16 v[66:69], v[176:179], v[242:245], 0
	v_mfma_f32_16x16x32_bf16 v[122:125], v[172:175], v[202:205], v[122:125]
	v_mfma_f32_16x16x32_bf16 v[114:117], v[194:197], v[202:205], v[114:117]
	v_mfma_f32_16x16x32_bf16 v[106:109], v[172:175], v[210:213], v[106:109]
	v_mfma_f32_16x16x32_bf16 v[98:101], v[194:197], v[210:213], v[98:101]
	v_mfma_f32_16x16x32_bf16 v[90:93], v[172:175], v[238:241], v[90:93]
	v_mfma_f32_16x16x32_bf16 v[82:85], v[194:197], v[238:241], v[82:85]
	v_mfma_f32_16x16x32_bf16 v[74:77], v[172:175], v[246:249], v[74:77]
	v_mfma_f32_16x16x32_bf16 v[66:69], v[194:197], v[246:249], v[66:69]
	s_setprio 0
	s_barrier
	s_add_i32 s58, s58, s24
	v_lshl_add_u64 v[148:149], s[8:9], 0, v[0:1]
	s_mov_b32 m0, s58
	ds_read_b128 v[198:201], v159 offset:16384
	ds_read_b128 v[202:205], v159 offset:17408
	ds_read_b128 v[206:209], v159 offset:18432
	ds_read_b128 v[210:213], v159 offset:19456
	ds_read_b128 v[234:237], v159 offset:20480
	ds_read_b128 v[238:241], v159 offset:21504
	ds_read_b128 v[242:245], v159 offset:22528
	ds_read_b128 v[246:249], v159 offset:23552
	global_load_lds_dwordx4 v[148:149], off
	s_add_i32 m0, s58, 0x2000
	s_add_u32 s58, s8, 0x80000
	v_lshl_add_u64 v[156:157], s[8:9], 0, v[130:131]
	s_addc_u32 s59, s9, 0
	s_add_i32 s73, s73, s24
	global_load_lds_dwordx4 v[156:157], off
	v_lshl_add_u64 v[214:215], s[58:59], 0, v[0:1]
	s_mov_b32 m0, s73
	v_lshl_add_u64 v[250:251], s[22:23], 0, v[132:133]
	global_load_lds_dwordx4 v[214:215], off
	v_lshl_add_u64 v[214:215], s[58:59], 0, v[130:131]
	s_add_i32 m0, s73, 0x2000
	s_nop 0
	global_load_lds_dwordx4 v[214:215], off
	v_lshl_add_u64 v[214:215], s[22:23], 0, v[134:135]
	s_mov_b32 m0, s25
	s_nop 0
	global_load_lds_dwordx4 v[214:215], off
	s_mov_b32 m0, s26
	s_nop 0
	global_load_lds_dwordx4 v[250:251], off
	s_waitcnt vmcnt(8)
	s_waitcnt lgkmcnt(0)
	s_barrier
; #define PG8_STAGE(bufoff, gbase, voff) do { _Pragma("unroll") for (int _i = 0; _i < 2; ++_i) \
;         __builtin_amdgcn_global_load_lds((const unsigned*)((const char*)(gbase) + (voff)[_i]), (LAS unsigned*)(lds + (bufoff) + ldsw + _i * 8192), 16, 0, 0); } while (0)
; #define PG8_LDA(dst, b, h) do { _Pragma("unroll") for (int m = 0; m < 4; ++m) _Pragma("unroll") for (int k = 0; k < 2; ++k) dst[m][k] = *(const LAS bf16x8*)(lds + PG8_SA(b, h) + aoff + m * 2048 + k * 1024); } while (0)
; #define PG8_LDB(dst, b, h) do { _Pragma("unroll") for (int n = 0; n < 2; ++n) _Pragma("unroll") for (int k = 0; k < 2; ++k) dst[n][k] = *(const LAS bf16x8*)(lds + PG8_SB(b, h) + boff + n * 2048 + k * 1024); } while (0)
; #define PG8_MMA(ai, bj, At, Bt) do { __builtin_amdgcn_s_setprio(1); _Pragma("unroll") for (int m = 0; m < 4; ++m) _Pragma("unroll") for (int n = 0; n < 2; ++n) _Pragma("unroll") for (int k = 0; k < 2; ++k) \
;         acc[ai][bj][m][n] = __builtin_amdgcn_mfma_f32_16x16x32_bf16(Bt[n][k], At[m][k], acc[ai][bj][m][n], 0, 0, 0); __builtin_amdgcn_s_setprio(0); } while (0)
; #define PG8_WAIT_V(n) asm volatile("s_waitcnt vmcnt(" #n ")" ::: "memory")
; #define PG8_WAIT_L(n) asm volatile("s_waitcnt lgkmcnt(" #n ")" ::: "memory")
; #define PG8_BAR __builtin_amdgcn_s_barrier()
; #define PG8_SCHED __builtin_amdgcn_sched_barrier(0)
; template <class Epi, class Sched, bool ALIGN_EPI = true, bool SP2 = true>
; __device__ __forceinline__ void gemm_phase(LAS unsigned char* lds, const Gemm g, const Sched& S, const Epi& E) {
;     ...
;             PG8_LDA(At, 0, 1); PG8_STAGE(PG8_SB(0, 0), b2, voffB); PG8_STAGE(PG8_SB(0, 1), b2 + hstep, voffB); PG8_STAGE(PG8_SA(0, 0), a2, voffA);
;             PG8_WAIT_V(8); PG8_WAIT_L(0); PG8_BAR; PG8_MMA(1, 0, At, B0); PG8_MMA(1, 1, At, B1); PG8_BAR; PG8_SCHED;
;             PG8_LDB(B0, 1, 0); PG8_LDB(B1, 1, 1); PG8_SCHED; PG8_LDA(At, 1, 0); PG8_STAGE(PG8_SA(0, 1), a2 + hstep, voffA);
;             PG8_WAIT_V(8); PG8_WAIT_L(0); PG8_BAR; PG8_MMA(0, 0, At, B0); PG8_MMA(0, 1, At, B1); PG8_BAR; PG8_SCHED;
	s_setprio 1
	s_waitcnt lgkmcnt(0)
	v_mfma_f32_16x16x32_bf16 v[62:65], v[140:143], v[198:201], 0
	v_mfma_f32_16x16x32_bf16 v[54:57], v[160:163], v[198:201], 0
	v_mfma_f32_16x16x32_bf16 v[46:49], v[140:143], v[206:209], 0
	v_mfma_f32_16x16x32_bf16 v[38:41], v[160:163], v[206:209], 0
	v_mfma_f32_16x16x32_bf16 v[30:33], v[140:143], v[234:237], 0
	v_mfma_f32_16x16x32_bf16 v[22:25], v[160:163], v[234:237], 0
	v_mfma_f32_16x16x32_bf16 v[14:17], v[140:143], v[242:245], 0
	v_mfma_f32_16x16x32_bf16 v[6:9], v[160:163], v[242:245], 0
	v_mfma_f32_16x16x32_bf16 v[62:65], v[144:147], v[202:205], v[62:65]
	v_mfma_f32_16x16x32_bf16 v[54:57], v[164:167], v[202:205], v[54:57]
	v_mfma_f32_16x16x32_bf16 v[46:49], v[144:147], v[210:213], v[46:49]
	v_mfma_f32_16x16x32_bf16 v[38:41], v[164:167], v[210:213], v[38:41]
	v_mfma_f32_16x16x32_bf16 v[30:33], v[144:147], v[238:241], v[30:33]
	v_mfma_f32_16x16x32_bf16 v[22:25], v[164:167], v[238:241], v[22:25]
	v_mfma_f32_16x16x32_bf16 v[14:17], v[144:147], v[246:249], v[14:17]
	v_mfma_f32_16x16x32_bf16 v[6:9], v[164:167], v[246:249], v[6:9]
	s_setprio 0
	s_setprio 1
	v_mfma_f32_16x16x32_bf16 v[58:61], v[168:171], v[198:201], 0
	v_mfma_f32_16x16x32_bf16 v[50:53], v[176:179], v[198:201], 0
	v_mfma_f32_16x16x32_bf16 v[42:45], v[168:171], v[206:209], 0
	v_mfma_f32_16x16x32_bf16 v[34:37], v[176:179], v[206:209], 0
	v_mfma_f32_16x16x32_bf16 v[26:29], v[168:171], v[234:237], 0
	v_mfma_f32_16x16x32_bf16 v[18:21], v[176:179], v[234:237], 0
	v_mfma_f32_16x16x32_bf16 v[10:13], v[168:171], v[242:245], 0
	v_mfma_f32_16x16x32_bf16 v[2:5], v[176:179], v[242:245], 0
	v_mfma_f32_16x16x32_bf16 v[58:61], v[172:175], v[202:205], v[58:61]
	v_mfma_f32_16x16x32_bf16 v[50:53], v[194:197], v[202:205], v[50:53]
	v_mfma_f32_16x16x32_bf16 v[42:45], v[172:175], v[210:213], v[42:45]
	v_mfma_f32_16x16x32_bf16 v[34:37], v[194:197], v[210:213], v[34:37]
	v_mfma_f32_16x16x32_bf16 v[26:29], v[172:175], v[238:241], v[26:29]
	v_mfma_f32_16x16x32_bf16 v[18:21], v[194:197], v[238:241], v[18:21]
	v_mfma_f32_16x16x32_bf16 v[10:13], v[172:175], v[246:249], v[10:13]
	v_mfma_f32_16x16x32_bf16 v[2:5], v[194:197], v[246:249], v[2:5]
	s_setprio 0
	s_barrier
	s_add_i32 s58, 0, 0x18000
	v_add_u32_e32 v150, s58, v153
	s_add_i32 s59, 0, 0x1c000
	ds_read_b128 v[140:143], v150
	ds_read_b128 v[144:147], v150 offset:1024
	ds_read_b128 v[160:163], v150 offset:2048
	ds_read_b128 v[164:167], v150 offset:3072
	v_add_u32_e32 v150, s59, v153
	ds_read_b128 v[168:171], v150
	ds_read_b128 v[172:175], v150 offset:1024
	ds_read_b128 v[176:179], v150 offset:2048
	ds_read_b128 v[194:197], v150 offset:3072
	s_add_u32 s22, s22, 0x80000
	s_addc_u32 s23, s23, 0
	s_mov_b32 m0, s27
	v_lshl_add_u64 v[224:225], s[22:23], 0, v[134:135]
	ds_read_b128 v[198:201], v159 offset:32768
	ds_read_b128 v[202:205], v159 offset:33792
	ds_read_b128 v[206:209], v159 offset:34816
	ds_read_b128 v[210:213], v159 offset:35840
	ds_read_b128 v[234:237], v159 offset:36864
	ds_read_b128 v[238:241], v159 offset:37888
	ds_read_b128 v[242:245], v159 offset:38912
	ds_read_b128 v[246:249], v159 offset:39936
	global_load_lds_dwordx4 v[224:225], off
	v_lshl_add_u64 v[224:225], s[22:23], 0, v[132:133]
	s_mov_b32 m0, s28
	s_nop 0
	global_load_lds_dwordx4 v[224:225], off
	s_waitcnt vmcnt(8)
	s_waitcnt lgkmcnt(0)
	s_barrier
	s_setprio 1
	s_waitcnt lgkmcnt(0)
	v_mfma_f32_16x16x32_bf16 v[126:129], v[140:143], v[198:201], v[126:129]
	v_mfma_f32_16x16x32_bf16 v[118:121], v[160:163], v[198:201], v[118:121]
	v_mfma_f32_16x16x32_bf16 v[110:113], v[140:143], v[206:209], v[110:113]
	v_mfma_f32_16x16x32_bf16 v[102:105], v[160:163], v[206:209], v[102:105]
	v_mfma_f32_16x16x32_bf16 v[94:97], v[140:143], v[234:237], v[94:97]
	v_mfma_f32_16x16x32_bf16 v[86:89], v[160:163], v[234:237], v[86:89]
	v_mfma_f32_16x16x32_bf16 v[78:81], v[140:143], v[242:245], v[78:81]
	v_mfma_f32_16x16x32_bf16 v[70:73], v[160:163], v[242:245], v[70:73]
	v_mfma_f32_16x16x32_bf16 v[126:129], v[144:147], v[202:205], v[126:129]
	v_mfma_f32_16x16x32_bf16 v[118:121], v[164:167], v[202:205], v[118:121]
	v_mfma_f32_16x16x32_bf16 v[110:113], v[144:147], v[210:213], v[110:113]
	v_mfma_f32_16x16x32_bf16 v[102:105], v[164:167], v[210:213], v[102:105]
	v_mfma_f32_16x16x32_bf16 v[94:97], v[144:147], v[238:241], v[94:97]
	v_mfma_f32_16x16x32_bf16 v[86:89], v[164:167], v[238:241], v[86:89]
	v_mfma_f32_16x16x32_bf16 v[78:81], v[144:147], v[246:249], v[78:81]
	v_mfma_f32_16x16x32_bf16 v[70:73], v[164:167], v[246:249], v[70:73]
	s_setprio 0
	s_setprio 1
	v_mfma_f32_16x16x32_bf16 v[122:125], v[168:171], v[198:201], v[122:125]
	v_mfma_f32_16x16x32_bf16 v[114:117], v[176:179], v[198:201], v[114:117]
	v_mfma_f32_16x16x32_bf16 v[106:109], v[168:171], v[206:209], v[106:109]
	v_mfma_f32_16x16x32_bf16 v[98:101], v[176:179], v[206:209], v[98:101]
	v_mfma_f32_16x16x32_bf16 v[90:93], v[168:171], v[234:237], v[90:93]
	v_mfma_f32_16x16x32_bf16 v[82:85], v[176:179], v[234:237], v[82:85]
	v_mfma_f32_16x16x32_bf16 v[74:77], v[168:171], v[242:245], v[74:77]
	v_mfma_f32_16x16x32_bf16 v[66:69], v[176:179], v[242:245], v[66:69]
	v_mfma_f32_16x16x32_bf16 v[122:125], v[172:175], v[202:205], v[122:125]
	v_mfma_f32_16x16x32_bf16 v[114:117], v[194:197], v[202:205], v[114:117]
	v_mfma_f32_16x16x32_bf16 v[106:109], v[172:175], v[210:213], v[106:109]
	v_mfma_f32_16x16x32_bf16 v[98:101], v[194:197], v[210:213], v[98:101]
	v_mfma_f32_16x16x32_bf16 v[90:93], v[172:175], v[238:241], v[90:93]
	v_mfma_f32_16x16x32_bf16 v[82:85], v[194:197], v[238:241], v[82:85]
	v_mfma_f32_16x16x32_bf16 v[74:77], v[172:175], v[246:249], v[74:77]
	v_mfma_f32_16x16x32_bf16 v[66:69], v[194:197], v[246:249], v[66:69]
	s_setprio 0
	s_barrier
; #define PG8_STAGE(bufoff, gbase, voff) do { _Pragma("unroll") for (int _i = 0; _i < 2; ++_i) \
;         __builtin_amdgcn_global_load_lds((const unsigned*)((const char*)(gbase) + (voff)[_i]), (LAS unsigned*)(lds + (bufoff) + ldsw + _i * 8192), 16, 0, 0); } while (0)
; #define PG8_LDA(dst, b, h) do { _Pragma("unroll") for (int m = 0; m < 4; ++m) _Pragma("unroll") for (int k = 0; k < 2; ++k) dst[m][k] = *(const LAS bf16x8*)(lds + PG8_SA(b, h) + aoff + m * 2048 + k * 1024); } while (0)
; #define PG8_MMA(ai, bj, At, Bt) do { __builtin_amdgcn_s_setprio(1); _Pragma("unroll") for (int m = 0; m < 4; ++m) _Pragma("unroll") for (int n = 0; n < 2; ++n) _Pragma("unroll") for (int k = 0; k < 2; ++k) \
;         acc[ai][bj][m][n] = __builtin_amdgcn_mfma_f32_16x16x32_bf16(Bt[n][k], At[m][k], acc[ai][bj][m][n], 0, 0, 0); __builtin_amdgcn_s_setprio(0); } while (0)
; #define PG8_WAIT_V(n) asm volatile("s_waitcnt vmcnt(" #n ")" ::: "memory")
; #define PG8_WAIT_L(n) asm volatile("s_waitcnt lgkmcnt(" #n ")" ::: "memory")
; #define PG8_BAR __builtin_amdgcn_s_barrier()
; #define PG8_SCHED __builtin_amdgcn_sched_barrier(0)
; template <class Epi, class Sched, bool ALIGN_EPI = true, bool SP2 = true>
; __device__ __forceinline__ void gemm_phase(LAS unsigned char* lds, const Gemm g, const Sched& S, const Epi& E) {
;     ...
;         for (int t = 0; t < nt; t += 2) {
;     ...
;             PG8_LDA(At, 1, 1); PG8_STAGE(PG8_SB(1, 0), b3, voffB); PG8_STAGE(PG8_SB(1, 1), b3 + hstep, voffB); PG8_STAGE(PG8_SA(1, 0), a3, voffA);
;             PG8_WAIT_V(8); PG8_WAIT_L(0); PG8_BAR; PG8_MMA(1, 0, At, B0); PG8_MMA(1, 1, At, B1); PG8_BAR; PG8_SCHED;
	s_add_i32 s22, s58, s24
	v_lshl_add_u64 v[148:149], v[148:149], 0, s[92:93]
	s_mov_b32 m0, s22
	ds_read_b128 v[198:201], v159 offset:49152
	ds_read_b128 v[202:205], v159 offset:50176
	ds_read_b128 v[206:209], v159 offset:51200
	ds_read_b128 v[210:213], v159 offset:52224
	ds_read_b128 v[234:237], v159 offset:53248
	ds_read_b128 v[238:241], v159 offset:54272
	ds_read_b128 v[242:245], v159 offset:55296
	ds_read_b128 v[246:249], v159 offset:56320
	global_load_lds_dwordx4 v[148:149], off
	s_add_i32 m0, s22, 0x2000
	s_add_u32 s8, s8, 0x80080
	v_lshl_add_u64 v[148:149], v[156:157], 0, s[92:93]
	s_addc_u32 s9, s9, 0
	s_add_i32 s22, s59, s24
	global_load_lds_dwordx4 v[148:149], off
	v_lshl_add_u64 v[148:149], s[8:9], 0, v[0:1]
	s_mov_b32 m0, s22
	s_nop 0
	global_load_lds_dwordx4 v[148:149], off
	v_lshl_add_u64 v[148:149], s[8:9], 0, v[130:131]
	s_add_i32 m0, s22, 0x2000
	s_nop 0
	global_load_lds_dwordx4 v[148:149], off
	v_lshl_add_u64 v[148:149], v[214:215], 0, s[92:93]
	s_mov_b32 m0, s29
	s_nop 0
	global_load_lds_dwordx4 v[148:149], off
	v_lshl_add_u64 v[148:149], v[250:251], 0, s[92:93]
	s_mov_b32 m0, s30
	s_nop 0
	global_load_lds_dwordx4 v[148:149], off
	s_waitcnt vmcnt(8)
	s_waitcnt lgkmcnt(0)
	s_barrier
	s_setprio 1
	s_waitcnt lgkmcnt(0)
	v_mfma_f32_16x16x32_bf16 v[62:65], v[140:143], v[198:201], v[62:65]
	v_mfma_f32_16x16x32_bf16 v[54:57], v[160:163], v[198:201], v[54:57]
	v_mfma_f32_16x16x32_bf16 v[46:49], v[140:143], v[206:209], v[46:49]
	v_mfma_f32_16x16x32_bf16 v[38:41], v[160:163], v[206:209], v[38:41]
	v_mfma_f32_16x16x32_bf16 v[30:33], v[140:143], v[234:237], v[30:33]
	v_mfma_f32_16x16x32_bf16 v[22:25], v[160:163], v[234:237], v[22:25]
	v_mfma_f32_16x16x32_bf16 v[14:17], v[140:143], v[242:245], v[14:17]
	v_mfma_f32_16x16x32_bf16 v[6:9], v[160:163], v[242:245], v[6:9]
	v_mfma_f32_16x16x32_bf16 v[62:65], v[144:147], v[202:205], v[62:65]
	v_mfma_f32_16x16x32_bf16 v[54:57], v[164:167], v[202:205], v[54:57]
	v_mfma_f32_16x16x32_bf16 v[46:49], v[144:147], v[210:213], v[46:49]
	v_mfma_f32_16x16x32_bf16 v[38:41], v[164:167], v[210:213], v[38:41]
	v_mfma_f32_16x16x32_bf16 v[30:33], v[144:147], v[238:241], v[30:33]
	v_mfma_f32_16x16x32_bf16 v[22:25], v[164:167], v[238:241], v[22:25]
	v_mfma_f32_16x16x32_bf16 v[14:17], v[144:147], v[246:249], v[14:17]
	v_mfma_f32_16x16x32_bf16 v[6:9], v[164:167], v[246:249], v[6:9]
	s_setprio 0
	s_setprio 1
	v_mfma_f32_16x16x32_bf16 v[58:61], v[168:171], v[198:201], v[58:61]
	v_mfma_f32_16x16x32_bf16 v[50:53], v[176:179], v[198:201], v[50:53]
	v_mfma_f32_16x16x32_bf16 v[42:45], v[168:171], v[206:209], v[42:45]
	v_mfma_f32_16x16x32_bf16 v[34:37], v[176:179], v[206:209], v[34:37]
	v_mfma_f32_16x16x32_bf16 v[26:29], v[168:171], v[234:237], v[26:29]
	v_mfma_f32_16x16x32_bf16 v[18:21], v[176:179], v[234:237], v[18:21]
	v_mfma_f32_16x16x32_bf16 v[10:13], v[168:171], v[242:245], v[10:13]
	v_mfma_f32_16x16x32_bf16 v[2:5], v[176:179], v[242:245], v[2:5]
	v_mfma_f32_16x16x32_bf16 v[58:61], v[172:175], v[202:205], v[58:61]
	v_mfma_f32_16x16x32_bf16 v[50:53], v[194:197], v[202:205], v[50:53]
	v_mfma_f32_16x16x32_bf16 v[42:45], v[172:175], v[210:213], v[42:45]
	v_mfma_f32_16x16x32_bf16 v[34:37], v[194:197], v[210:213], v[34:37]
	v_mfma_f32_16x16x32_bf16 v[26:29], v[172:175], v[238:241], v[26:29]
	v_mfma_f32_16x16x32_bf16 v[18:21], v[194:197], v[238:241], v[18:21]
	v_mfma_f32_16x16x32_bf16 v[10:13], v[172:175], v[246:249], v[10:13]
	v_mfma_f32_16x16x32_bf16 v[2:5], v[194:197], v[246:249], v[2:5]
	s_setprio 0
	s_barrier
	s_add_i32 s72, s72, 2
	s_add_u32 s6, s6, 0x100
	s_addc_u32 s7, s7, 0
	s_add_u32 s70, s70, 0x100
	s_addc_u32 s71, s71, 0
	s_cmp_gt_u32 s72, 29

; #define PG8_STAGE(bufoff, gbase, voff) do { _Pragma("unroll") for (int _i = 0; _i < 2; ++_i) \
;         __builtin_amdgcn_global_load_lds((const unsigned*)((const char*)(gbase) + (voff)[_i]), (LAS unsigned*)(lds + (bufoff) + ldsw + _i * 8192), 16, 0, 0); } while (0)
; #define PG8_LDA(dst, b, h) do { _Pragma("unroll") for (int m = 0; m < 4; ++m) _Pragma("unroll") for (int k = 0; k < 2; ++k) dst[m][k] = *(const LAS bf16x8*)(lds + PG8_SA(b, h) + aoff + m * 2048 + k * 1024); } while (0)
; #define PG8_LDB(dst, b, h) do { _Pragma("unroll") for (int n = 0; n < 2; ++n) _Pragma("unroll") for (int k = 0; k < 2; ++k) dst[n][k] = *(const LAS bf16x8*)(lds + PG8_SB(b, h) + boff + n * 2048 + k * 1024); } while (0)
; #define PG8_MMA(ai, bj, At, Bt) do { __builtin_amdgcn_s_setprio(1); _Pragma("unroll") for (int m = 0; m < 4; ++m) _Pragma("unroll") for (int n = 0; n < 2; ++n) _Pragma("unroll") for (int k = 0; k < 2; ++k) \
;         acc[ai][bj][m][n] = __builtin_amdgcn_mfma_f32_16x16x32_bf16(Bt[n][k], At[m][k], acc[ai][bj][m][n], 0, 0, 0); __builtin_amdgcn_s_setprio(0); } while (0)
; #define PG8_WAIT_V(n) asm volatile("s_waitcnt vmcnt(" #n ")" ::: "memory")
; #define PG8_WAIT_L(n) asm volatile("s_waitcnt lgkmcnt(" #n ")" ::: "memory")
; #define PG8_BAR __builtin_amdgcn_s_barrier()
; template <class Epi, class Sched, bool ALIGN_EPI = true, bool SP2 = true>
; __device__ __forceinline__ void gemm_phase(LAS unsigned char* lds, const Gemm g, const Sched& S, const Epi& E) {
;     ...
;         for (int t = 0; t < nt; t += 2) {
;             const bool last = (t == nt - 2);
;             const char* a1 = cA + (size_t)(t + 1) * kstep;
;             const char* a2 = last ? nA : cA + (size_t)(t + 2) * kstep; const char* b2 = last ? nB : cB + (size_t)(t + 2) * kstep;
;             const char* a3 = a2 + kstep; const char* b3 = b2 + kstep;
;             if constexpr (SP2) {
;             PG8_LDB(B0, 0, 0); PG8_LDB(B1, 0, 1); PG8_SCHED; PG8_LDA(At, 0, 0); PG8_STAGE(PG8_SA(1, 1), a1 + hstep, voffA);
;             PG8_WAIT_V(8); PG8_WAIT_L(0); PG8_BAR; PG8_MMA(0, 0, At, B0); PG8_MMA(0, 1, At, B1); PG8_BAR; PG8_SCHED;
;             PG8_LDA(At, 0, 1); PG8_STAGE(PG8_SB(0, 0), b2, voffB); PG8_STAGE(PG8_SB(0, 1), b2 + hstep, voffB); PG8_STAGE(PG8_SA(0, 0), a2, voffA);
;             PG8_WAIT_V(8); PG8_WAIT_L(0); PG8_BAR; PG8_MMA(1, 0, At, B0); PG8_MMA(1, 1, At, B1); PG8_BAR; PG8_SCHED;
.LBB0_185:
	s_add_u32 s56, s6, 0x100
	s_addc_u32 s57, s7, 0
	s_mov_b32 s72, -2
	s_waitcnt lgkmcnt(0)
	s_add_u32 s6, s4, 0x100
	s_addc_u32 s7, s5, 0
	s_add_i32 s58, 0, 0x10000
	s_cmpk_eq_i32 s72, 0x54
	s_cselect_b32 s15, s1, s7
	s_cselect_b32 s14, s0, s6
	s_cselect_b32 s9, s31, s57
	s_cselect_b32 s8, s30, s56
	s_add_i32 s59, 0, 0x14000
	v_add_u32_e32 v142, s58, v208
	v_add_u32_e32 v164, s59, v208
	ds_read_b128 v[130:133], v142
	ds_read_b128 v[134:137], v142 offset:1024
	ds_read_b128 v[138:141], v142 offset:2048
	ds_read_b128 v[142:145], v142 offset:3072
	ds_read_b128 v[152:155], v164
	ds_read_b128 v[156:159], v164 offset:1024
	ds_read_b128 v[160:163], v164 offset:2048
	ds_read_b128 v[164:167], v164 offset:3072
	v_lshl_add_u64 v[206:207], s[4:5], 0, v[148:149]
	s_add_i32 m0, s71, 0xc000
	ds_read_b128 v[168:171], v210
	ds_read_b128 v[172:175], v210 offset:1024
	ds_read_b128 v[176:179], v210 offset:2048
	ds_read_b128 v[194:197], v210 offset:3072
	ds_read_b128 v[198:201], v210 offset:4096
	ds_read_b128 v[202:205], v210 offset:5120
	ds_read_b128 v[212:215], v210 offset:6144
	ds_read_b128 v[234:237], v210 offset:7168
	global_load_lds_dwordx4 v[206:207], off
	v_lshl_add_u64 v[206:207], s[4:5], 0, v[150:151]
	s_add_i32 m0, s71, 0xe000
	s_nop 0
	global_load_lds_dwordx4 v[206:207], off
	s_waitcnt vmcnt(8)
	s_waitcnt lgkmcnt(0)
	s_barrier
	s_setprio 1
	s_waitcnt lgkmcnt(0)
	v_mfma_f32_16x16x32_bf16 v[126:129], v[130:133], v[168:171], 0
	v_mfma_f32_16x16x32_bf16 v[122:125], v[138:141], v[168:171], 0
	v_mfma_f32_16x16x32_bf16 v[110:113], v[130:133], v[176:179], 0
	v_mfma_f32_16x16x32_bf16 v[106:109], v[138:141], v[176:179], 0
	v_mfma_f32_16x16x32_bf16 v[94:97], v[130:133], v[198:201], 0
	v_mfma_f32_16x16x32_bf16 v[90:93], v[138:141], v[198:201], 0
	v_mfma_f32_16x16x32_bf16 v[78:81], v[130:133], v[212:215], 0
	v_mfma_f32_16x16x32_bf16 v[74:77], v[138:141], v[212:215], 0
	v_mfma_f32_16x16x32_bf16 v[126:129], v[134:137], v[172:175], v[126:129]
	v_mfma_f32_16x16x32_bf16 v[122:125], v[142:145], v[172:175], v[122:125]
	v_mfma_f32_16x16x32_bf16 v[110:113], v[134:137], v[194:197], v[110:113]
	v_mfma_f32_16x16x32_bf16 v[106:109], v[142:145], v[194:197], v[106:109]
	v_mfma_f32_16x16x32_bf16 v[94:97], v[134:137], v[202:205], v[94:97]
	v_mfma_f32_16x16x32_bf16 v[90:93], v[142:145], v[202:205], v[90:93]
	v_mfma_f32_16x16x32_bf16 v[78:81], v[134:137], v[234:237], v[78:81]
	v_mfma_f32_16x16x32_bf16 v[74:77], v[142:145], v[234:237], v[74:77]
	s_setprio 0
	s_setprio 1
	v_mfma_f32_16x16x32_bf16 v[118:121], v[152:155], v[168:171], 0
	v_mfma_f32_16x16x32_bf16 v[114:117], v[160:163], v[168:171], 0
	v_mfma_f32_16x16x32_bf16 v[102:105], v[152:155], v[176:179], 0
	v_mfma_f32_16x16x32_bf16 v[98:101], v[160:163], v[176:179], 0
	v_mfma_f32_16x16x32_bf16 v[86:89], v[152:155], v[198:201], 0
	v_mfma_f32_16x16x32_bf16 v[82:85], v[160:163], v[198:201], 0
	v_mfma_f32_16x16x32_bf16 v[70:73], v[152:155], v[212:215], 0
	v_mfma_f32_16x16x32_bf16 v[66:69], v[160:163], v[212:215], 0
	v_mfma_f32_16x16x32_bf16 v[118:121], v[156:159], v[172:175], v[118:121]
	v_mfma_f32_16x16x32_bf16 v[114:117], v[164:167], v[172:175], v[114:117]
	v_mfma_f32_16x16x32_bf16 v[102:105], v[156:159], v[194:197], v[102:105]
	v_mfma_f32_16x16x32_bf16 v[98:101], v[164:167], v[194:197], v[98:101]
	v_mfma_f32_16x16x32_bf16 v[86:89], v[156:159], v[202:205], v[86:89]
	v_mfma_f32_16x16x32_bf16 v[82:85], v[164:167], v[202:205], v[82:85]
	v_mfma_f32_16x16x32_bf16 v[70:73], v[156:159], v[234:237], v[70:73]
	v_mfma_f32_16x16x32_bf16 v[66:69], v[164:167], v[234:237], v[66:69]
	s_setprio 0
	s_barrier
	s_add_i32 s4, s58, s70
	v_lshl_add_u64 v[206:207], s[8:9], 0, v[0:1]
	s_mov_b32 m0, s4
	ds_read_b128 v[168:171], v210 offset:16384
	ds_read_b128 v[172:175], v210 offset:17408
	ds_read_b128 v[176:179], v210 offset:18432
	ds_read_b128 v[194:197], v210 offset:19456
	ds_read_b128 v[198:201], v210 offset:20480
	ds_read_b128 v[202:205], v210 offset:21504
	ds_read_b128 v[212:215], v210 offset:22528
	ds_read_b128 v[234:237], v210 offset:23552
	global_load_lds_dwordx4 v[206:207], off
	s_add_i32 m0, s4, 0x2000
	s_add_u32 s4, s8, 0x160000
	v_lshl_add_u64 v[224:225], s[8:9], 0, v[146:147]
	s_addc_u32 s5, s9, 0
	s_add_i32 s58, s59, s70
	global_load_lds_dwordx4 v[224:225], off
	v_lshl_add_u64 v[238:239], s[4:5], 0, v[0:1]
	s_mov_b32 m0, s58
	v_lshl_add_u64 v[240:241], s[14:15], 0, v[146:147]
	global_load_lds_dwordx4 v[238:239], off
	v_lshl_add_u64 v[238:239], s[4:5], 0, v[146:147]
	s_add_i32 m0, s58, 0x2000
	s_nop 0
	global_load_lds_dwordx4 v[238:239], off
	v_lshl_add_u64 v[238:239], s[14:15], 0, v[0:1]
	s_mov_b32 m0, s71
	s_nop 0
	global_load_lds_dwordx4 v[238:239], off
	s_mov_b32 m0, s74
	s_nop 0
	global_load_lds_dwordx4 v[240:241], off
	s_waitcnt vmcnt(8)
	s_waitcnt lgkmcnt(0)
	s_barrier
; #define PG8_STAGE(bufoff, gbase, voff) do { _Pragma("unroll") for (int _i = 0; _i < 2; ++_i) \
;         __builtin_amdgcn_global_load_lds((const unsigned*)((const char*)(gbase) + (voff)[_i]), (LAS unsigned*)(lds + (bufoff) + ldsw + _i * 8192), 16, 0, 0); } while (0)
; #define PG8_LDA(dst, b, h) do { _Pragma("unroll") for (int m = 0; m < 4; ++m) _Pragma("unroll") for (int k = 0; k < 2; ++k) dst[m][k] = *(const LAS bf16x8*)(lds + PG8_SA(b, h) + aoff + m * 2048 + k * 1024); } while (0)
; #define PG8_LDB(dst, b, h) do { _Pragma("unroll") for (int n = 0; n < 2; ++n) _Pragma("unroll") for (int k = 0; k < 2; ++k) dst[n][k] = *(const LAS bf16x8*)(lds + PG8_SB(b, h) + boff + n * 2048 + k * 1024); } while (0)
; #define PG8_MMA(ai, bj, At, Bt) do { __builtin_amdgcn_s_setprio(1); _Pragma("unroll") for (int m = 0; m < 4; ++m) _Pragma("unroll") for (int n = 0; n < 2; ++n) _Pragma("unroll") for (int k = 0; k < 2; ++k) \
;         acc[ai][bj][m][n] = __builtin_amdgcn_mfma_f32_16x16x32_bf16(Bt[n][k], At[m][k], acc[ai][bj][m][n], 0, 0, 0); __builtin_amdgcn_s_setprio(0); } while (0)
; #define PG8_WAIT_V(n) asm volatile("s_waitcnt vmcnt(" #n ")" ::: "memory")
; #define PG8_WAIT_L(n) asm volatile("s_waitcnt lgkmcnt(" #n ")" ::: "memory")
; #define PG8_BAR __builtin_amdgcn_s_barrier()
; #define PG8_SCHED __builtin_amdgcn_sched_barrier(0)
; template <class Epi, class Sched, bool ALIGN_EPI = true, bool SP2 = true>
; __device__ __forceinline__ void gemm_phase(LAS unsigned char* lds, const Gemm g, const Sched& S, const Epi& E) {
;     ...
;             PG8_LDA(At, 0, 1); PG8_STAGE(PG8_SB(0, 0), b2, voffB); PG8_STAGE(PG8_SB(0, 1), b2 + hstep, voffB); PG8_STAGE(PG8_SA(0, 0), a2, voffA);
;             PG8_WAIT_V(8); PG8_WAIT_L(0); PG8_BAR; PG8_MMA(1, 0, At, B0); PG8_MMA(1, 1, At, B1); PG8_BAR; PG8_SCHED;
;             PG8_LDB(B0, 1, 0); PG8_LDB(B1, 1, 1); PG8_SCHED; PG8_LDA(At, 1, 0); PG8_STAGE(PG8_SA(0, 1), a2 + hstep, voffA);
;             PG8_WAIT_V(8); PG8_WAIT_L(0); PG8_BAR; PG8_MMA(0, 0, At, B0); PG8_MMA(0, 1, At, B1); PG8_BAR; PG8_SCHED;
	s_setprio 1
	s_waitcnt lgkmcnt(0)
	v_mfma_f32_16x16x32_bf16 v[62:65], v[130:133], v[168:171], 0
	v_mfma_f32_16x16x32_bf16 v[58:61], v[138:141], v[168:171], 0
	v_mfma_f32_16x16x32_bf16 v[46:49], v[130:133], v[176:179], 0
	v_mfma_f32_16x16x32_bf16 v[42:45], v[138:141], v[176:179], 0
	v_mfma_f32_16x16x32_bf16 v[30:33], v[130:133], v[198:201], 0
	v_mfma_f32_16x16x32_bf16 v[26:29], v[138:141], v[198:201], 0
	v_mfma_f32_16x16x32_bf16 v[14:17], v[130:133], v[212:215], 0
	v_mfma_f32_16x16x32_bf16 v[10:13], v[138:141], v[212:215], 0
	v_mfma_f32_16x16x32_bf16 v[62:65], v[134:137], v[172:175], v[62:65]
	v_mfma_f32_16x16x32_bf16 v[58:61], v[142:145], v[172:175], v[58:61]
	v_mfma_f32_16x16x32_bf16 v[46:49], v[134:137], v[194:197], v[46:49]
	v_mfma_f32_16x16x32_bf16 v[42:45], v[142:145], v[194:197], v[42:45]
	v_mfma_f32_16x16x32_bf16 v[30:33], v[134:137], v[202:205], v[30:33]
	v_mfma_f32_16x16x32_bf16 v[26:29], v[142:145], v[202:205], v[26:29]
	v_mfma_f32_16x16x32_bf16 v[14:17], v[134:137], v[234:237], v[14:17]
	v_mfma_f32_16x16x32_bf16 v[10:13], v[142:145], v[234:237], v[10:13]
	s_setprio 0
	s_setprio 1
	v_mfma_f32_16x16x32_bf16 v[54:57], v[152:155], v[168:171], 0
	v_mfma_f32_16x16x32_bf16 v[50:53], v[160:163], v[168:171], 0
	v_mfma_f32_16x16x32_bf16 v[38:41], v[152:155], v[176:179], 0
	v_mfma_f32_16x16x32_bf16 v[34:37], v[160:163], v[176:179], 0
	v_mfma_f32_16x16x32_bf16 v[22:25], v[152:155], v[198:201], 0
	v_mfma_f32_16x16x32_bf16 v[18:21], v[160:163], v[198:201], 0
	v_mfma_f32_16x16x32_bf16 v[6:9], v[152:155], v[212:215], 0
	v_mfma_f32_16x16x32_bf16 v[2:5], v[160:163], v[212:215], 0
	v_mfma_f32_16x16x32_bf16 v[54:57], v[156:159], v[172:175], v[54:57]
	v_mfma_f32_16x16x32_bf16 v[50:53], v[164:167], v[172:175], v[50:53]
	v_mfma_f32_16x16x32_bf16 v[38:41], v[156:159], v[194:197], v[38:41]
	v_mfma_f32_16x16x32_bf16 v[34:37], v[164:167], v[194:197], v[34:37]
	v_mfma_f32_16x16x32_bf16 v[22:25], v[156:159], v[202:205], v[22:25]
	v_mfma_f32_16x16x32_bf16 v[18:21], v[164:167], v[202:205], v[18:21]
	v_mfma_f32_16x16x32_bf16 v[6:9], v[156:159], v[234:237], v[6:9]
	v_mfma_f32_16x16x32_bf16 v[2:5], v[164:167], v[234:237], v[2:5]
	s_setprio 0
	s_barrier
	s_add_i32 s58, 0, 0x18000
	s_add_i32 s59, 0, 0x1c000
	v_add_u32_e32 v142, s58, v208
	v_add_u32_e32 v164, s59, v208
	ds_read_b128 v[130:133], v142
	ds_read_b128 v[134:137], v142 offset:1024
	ds_read_b128 v[138:141], v142 offset:2048
	ds_read_b128 v[142:145], v142 offset:3072
	ds_read_b128 v[152:155], v164
	ds_read_b128 v[156:159], v164 offset:1024
	ds_read_b128 v[160:163], v164 offset:2048
	ds_read_b128 v[164:167], v164 offset:3072
	s_add_u32 s4, s14, 0x160000
	s_addc_u32 s5, s15, 0
	s_mov_b32 m0, s75
	v_lshl_add_u64 v[242:243], s[4:5], 0, v[0:1]
	ds_read_b128 v[168:171], v210 offset:32768
	ds_read_b128 v[172:175], v210 offset:33792
	ds_read_b128 v[176:179], v210 offset:34816
	ds_read_b128 v[194:197], v210 offset:35840
	ds_read_b128 v[198:201], v210 offset:36864
	ds_read_b128 v[202:205], v210 offset:37888
	ds_read_b128 v[212:215], v210 offset:38912
	ds_read_b128 v[234:237], v210 offset:39936
	global_load_lds_dwordx4 v[242:243], off
	v_lshl_add_u64 v[242:243], s[4:5], 0, v[146:147]
	s_mov_b32 m0, s76
	s_nop 0
	global_load_lds_dwordx4 v[242:243], off
	s_waitcnt vmcnt(8)
	s_waitcnt lgkmcnt(0)
	s_barrier
	s_setprio 1
	s_waitcnt lgkmcnt(0)
	v_mfma_f32_16x16x32_bf16 v[126:129], v[130:133], v[168:171], v[126:129]
	v_mfma_f32_16x16x32_bf16 v[122:125], v[138:141], v[168:171], v[122:125]
	v_mfma_f32_16x16x32_bf16 v[110:113], v[130:133], v[176:179], v[110:113]
	v_mfma_f32_16x16x32_bf16 v[106:109], v[138:141], v[176:179], v[106:109]
	v_mfma_f32_16x16x32_bf16 v[94:97], v[130:133], v[198:201], v[94:97]
	v_mfma_f32_16x16x32_bf16 v[90:93], v[138:141], v[198:201], v[90:93]
	v_mfma_f32_16x16x32_bf16 v[78:81], v[130:133], v[212:215], v[78:81]
	v_mfma_f32_16x16x32_bf16 v[74:77], v[138:141], v[212:215], v[74:77]
	v_mfma_f32_16x16x32_bf16 v[126:129], v[134:137], v[172:175], v[126:129]
	v_mfma_f32_16x16x32_bf16 v[122:125], v[142:145], v[172:175], v[122:125]
	v_mfma_f32_16x16x32_bf16 v[110:113], v[134:137], v[194:197], v[110:113]
	v_mfma_f32_16x16x32_bf16 v[106:109], v[142:145], v[194:197], v[106:109]
	v_mfma_f32_16x16x32_bf16 v[94:97], v[134:137], v[202:205], v[94:97]
	v_mfma_f32_16x16x32_bf16 v[90:93], v[142:145], v[202:205], v[90:93]
	v_mfma_f32_16x16x32_bf16 v[78:81], v[134:137], v[234:237], v[78:81]
	v_mfma_f32_16x16x32_bf16 v[74:77], v[142:145], v[234:237], v[74:77]
	s_setprio 0
	s_setprio 1
	v_mfma_f32_16x16x32_bf16 v[118:121], v[152:155], v[168:171], v[118:121]
	v_mfma_f32_16x16x32_bf16 v[114:117], v[160:163], v[168:171], v[114:117]
	v_mfma_f32_16x16x32_bf16 v[102:105], v[152:155], v[176:179], v[102:105]
	v_mfma_f32_16x16x32_bf16 v[98:101], v[160:163], v[176:179], v[98:101]
	v_mfma_f32_16x16x32_bf16 v[86:89], v[152:155], v[198:201], v[86:89]
	v_mfma_f32_16x16x32_bf16 v[82:85], v[160:163], v[198:201], v[82:85]
	v_mfma_f32_16x16x32_bf16 v[70:73], v[152:155], v[212:215], v[70:73]
	v_mfma_f32_16x16x32_bf16 v[66:69], v[160:163], v[212:215], v[66:69]
	v_mfma_f32_16x16x32_bf16 v[118:121], v[156:159], v[172:175], v[118:121]
	v_mfma_f32_16x16x32_bf16 v[114:117], v[164:167], v[172:175], v[114:117]
	v_mfma_f32_16x16x32_bf16 v[102:105], v[156:159], v[194:197], v[102:105]
	v_mfma_f32_16x16x32_bf16 v[98:101], v[164:167], v[194:197], v[98:101]
	v_mfma_f32_16x16x32_bf16 v[86:89], v[156:159], v[202:205], v[86:89]
	v_mfma_f32_16x16x32_bf16 v[82:85], v[164:167], v[202:205], v[82:85]
	v_mfma_f32_16x16x32_bf16 v[70:73], v[156:159], v[234:237], v[70:73]
	v_mfma_f32_16x16x32_bf16 v[66:69], v[164:167], v[234:237], v[66:69]
	s_setprio 0
	s_barrier
; #define PG8_STAGE(bufoff, gbase, voff) do { _Pragma("unroll") for (int _i = 0; _i < 2; ++_i) \
;         __builtin_amdgcn_global_load_lds((const unsigned*)((const char*)(gbase) + (voff)[_i]), (LAS unsigned*)(lds + (bufoff) + ldsw + _i * 8192), 16, 0, 0); } while (0)
; #define PG8_LDA(dst, b, h) do { _Pragma("unroll") for (int m = 0; m < 4; ++m) _Pragma("unroll") for (int k = 0; k < 2; ++k) dst[m][k] = *(const LAS bf16x8*)(lds + PG8_SA(b, h) + aoff + m * 2048 + k * 1024); } while (0)
; #define PG8_MMA(ai, bj, At, Bt) do { __builtin_amdgcn_s_setprio(1); _Pragma("unroll") for (int m = 0; m < 4; ++m) _Pragma("unroll") for (int n = 0; n < 2; ++n) _Pragma("unroll") for (int k = 0; k < 2; ++k) \
;         acc[ai][bj][m][n] = __builtin_amdgcn_mfma_f32_16x16x32_bf16(Bt[n][k], At[m][k], acc[ai][bj][m][n], 0, 0, 0); __builtin_amdgcn_s_setprio(0); } while (0)
; #define PG8_WAIT_V(n) asm volatile("s_waitcnt vmcnt(" #n ")" ::: "memory")
; #define PG8_WAIT_L(n) asm volatile("s_waitcnt lgkmcnt(" #n ")" ::: "memory")
; #define PG8_BAR __builtin_amdgcn_s_barrier()
; #define PG8_SCHED __builtin_amdgcn_sched_barrier(0)
; template <class Epi, class Sched, bool ALIGN_EPI = true, bool SP2 = true>
; __device__ __forceinline__ void gemm_phase(LAS unsigned char* lds, const Gemm g, const Sched& S, const Epi& E) {
;     ...
;         for (int t = 0; t < nt; t += 2) {
;     ...
;             PG8_LDA(At, 1, 1); PG8_STAGE(PG8_SB(1, 0), b3, voffB); PG8_STAGE(PG8_SB(1, 1), b3 + hstep, voffB); PG8_STAGE(PG8_SA(1, 0), a3, voffA);
;             PG8_WAIT_V(8); PG8_WAIT_L(0); PG8_BAR; PG8_MMA(1, 0, At, B0); PG8_MMA(1, 1, At, B1); PG8_BAR; PG8_SCHED;
	s_add_i32 s4, s58, s70
	v_lshl_add_u64 v[206:207], v[206:207], 0, s[92:93]
	s_mov_b32 m0, s4
	ds_read_b128 v[168:171], v210 offset:49152
	ds_read_b128 v[172:175], v210 offset:50176
	ds_read_b128 v[176:179], v210 offset:51200
	ds_read_b128 v[194:197], v210 offset:52224
	ds_read_b128 v[198:201], v210 offset:53248
	ds_read_b128 v[202:205], v210 offset:54272
	ds_read_b128 v[212:215], v210 offset:55296
	ds_read_b128 v[234:237], v210 offset:56320
	global_load_lds_dwordx4 v[206:207], off
	s_add_i32 m0, s4, 0x2000
	s_add_u32 s4, s8, 0x160080
	v_lshl_add_u64 v[206:207], v[224:225], 0, s[92:93]
	s_addc_u32 s5, s9, 0
	s_add_i32 s8, s59, s70
	global_load_lds_dwordx4 v[206:207], off
	v_lshl_add_u64 v[206:207], s[4:5], 0, v[0:1]
	s_mov_b32 m0, s8
	s_nop 0
	global_load_lds_dwordx4 v[206:207], off
	v_lshl_add_u64 v[206:207], s[4:5], 0, v[146:147]
	s_add_i32 m0, s8, 0x2000
	s_nop 0
	global_load_lds_dwordx4 v[206:207], off
	v_lshl_add_u64 v[206:207], v[238:239], 0, s[92:93]
	s_mov_b32 m0, s78
	s_nop 0
	global_load_lds_dwordx4 v[206:207], off
	v_lshl_add_u64 v[206:207], v[240:241], 0, s[92:93]
	s_mov_b32 m0, s96
	s_nop 0
	global_load_lds_dwordx4 v[206:207], off
	s_waitcnt vmcnt(8)
	s_waitcnt lgkmcnt(0)
	s_barrier
	s_setprio 1
	s_waitcnt lgkmcnt(0)
	v_mfma_f32_16x16x32_bf16 v[62:65], v[130:133], v[168:171], v[62:65]
	v_mfma_f32_16x16x32_bf16 v[58:61], v[138:141], v[168:171], v[58:61]
	v_mfma_f32_16x16x32_bf16 v[46:49], v[130:133], v[176:179], v[46:49]
	v_mfma_f32_16x16x32_bf16 v[42:45], v[138:141], v[176:179], v[42:45]
	v_mfma_f32_16x16x32_bf16 v[30:33], v[130:133], v[198:201], v[30:33]
	v_mfma_f32_16x16x32_bf16 v[26:29], v[138:141], v[198:201], v[26:29]
	v_mfma_f32_16x16x32_bf16 v[14:17], v[130:133], v[212:215], v[14:17]
	v_mfma_f32_16x16x32_bf16 v[10:13], v[138:141], v[212:215], v[10:13]
	v_mfma_f32_16x16x32_bf16 v[62:65], v[134:137], v[172:175], v[62:65]
	v_mfma_f32_16x16x32_bf16 v[58:61], v[142:145], v[172:175], v[58:61]
	v_mfma_f32_16x16x32_bf16 v[46:49], v[134:137], v[194:197], v[46:49]
	v_mfma_f32_16x16x32_bf16 v[42:45], v[142:145], v[194:197], v[42:45]
	v_mfma_f32_16x16x32_bf16 v[30:33], v[134:137], v[202:205], v[30:33]
	v_mfma_f32_16x16x32_bf16 v[26:29], v[142:145], v[202:205], v[26:29]
	v_mfma_f32_16x16x32_bf16 v[14:17], v[134:137], v[234:237], v[14:17]
	v_mfma_f32_16x16x32_bf16 v[10:13], v[142:145], v[234:237], v[10:13]
	s_setprio 0
	s_setprio 1
	v_mfma_f32_16x16x32_bf16 v[54:57], v[152:155], v[168:171], v[54:57]
	v_mfma_f32_16x16x32_bf16 v[50:53], v[160:163], v[168:171], v[50:53]
	v_mfma_f32_16x16x32_bf16 v[38:41], v[152:155], v[176:179], v[38:41]
	v_mfma_f32_16x16x32_bf16 v[34:37], v[160:163], v[176:179], v[34:37]
	v_mfma_f32_16x16x32_bf16 v[22:25], v[152:155], v[198:201], v[22:25]
	v_mfma_f32_16x16x32_bf16 v[18:21], v[160:163], v[198:201], v[18:21]
	v_mfma_f32_16x16x32_bf16 v[6:9], v[152:155], v[212:215], v[6:9]
	v_mfma_f32_16x16x32_bf16 v[2:5], v[160:163], v[212:215], v[2:5]
	v_mfma_f32_16x16x32_bf16 v[54:57], v[156:159], v[172:175], v[54:57]
	v_mfma_f32_16x16x32_bf16 v[50:53], v[164:167], v[172:175], v[50:53]
	v_mfma_f32_16x16x32_bf16 v[38:41], v[156:159], v[194:197], v[38:41]
	v_mfma_f32_16x16x32_bf16 v[34:37], v[164:167], v[194:197], v[34:37]
	v_mfma_f32_16x16x32_bf16 v[22:25], v[156:159], v[202:205], v[22:25]
	v_mfma_f32_16x16x32_bf16 v[18:21], v[164:167], v[202:205], v[18:21]
	v_mfma_f32_16x16x32_bf16 v[6:9], v[156:159], v[234:237], v[6:9]
	v_mfma_f32_16x16x32_bf16 v[2:5], v[164:167], v[234:237], v[2:5]
	s_setprio 0
	s_barrier
	s_add_i32 s72, s72, 2
	s_add_u32 s56, s56, 0x100
	s_addc_u32 s57, s57, 0
	s_cmpk_gt_u32 s72, 0x55
	s_mov_b64 s[4:5], s[6:7]

;     __device__ bool next(int i, Unit& u) const { if (!so.next(i >> 1, u)) return false; u.kind = i & 1; return true; }
; #define PG8_STAGE(bufoff, gbase, voff) do { _Pragma("unroll") for (int _i = 0; _i < 2; ++_i) \
;         __builtin_amdgcn_global_load_lds((const unsigned*)((const char*)(gbase) + (voff)[_i]), (LAS unsigned*)(lds + (bufoff) + ldsw + _i * 8192), 16, 0, 0); } while (0)
; #define PG8_LDA(dst, b, h) do { _Pragma("unroll") for (int m = 0; m < 4; ++m) _Pragma("unroll") for (int k = 0; k < 2; ++k) dst[m][k] = *(const LAS bf16x8*)(lds + PG8_SA(b, h) + aoff + m * 2048 + k * 1024); } while (0)
; #define PG8_LDB(dst, b, h) do { _Pragma("unroll") for (int n = 0; n < 2; ++n) _Pragma("unroll") for (int k = 0; k < 2; ++k) dst[n][k] = *(const LAS bf16x8*)(lds + PG8_SB(b, h) + boff + n * 2048 + k * 1024); } while (0)
; #define PG8_WAIT_V(n) asm volatile("s_waitcnt vmcnt(" #n ")" ::: "memory")
; #define PG8_WAIT_L(n) asm volatile("s_waitcnt lgkmcnt(" #n ")" ::: "memory")
; #define PG8_BAR __builtin_amdgcn_s_barrier()
; template <class Epi, class Sched, bool ALIGN_EPI = true, bool SP2 = true>
; __device__ __forceinline__ void gemm_phase(LAS unsigned char* lds, const Gemm g, const Sched& S, const Epi& E) {
;     ...
;         const bool has_next = S.next(ui + 1, nxt);
;         const char* nA = has_next ? (const char*)(nxt.kind ? g.A1 : g.A0) + (size_t)nxt.pm * tstep : cA; const char* nB = has_next ? (const char*)(nxt.kind ? g.B1 : g.B0) + (size_t)nxt.pn * tstep : cB;
;         for (int t = 0; t < nt; t += 2) {
;             const bool last = (t == nt - 2);
;             const char* a1 = cA + (size_t)(t + 1) * kstep;
;             const char* a2 = last ? nA : cA + (size_t)(t + 2) * kstep; const char* b2 = last ? nB : cB + (size_t)(t + 2) * kstep;
;             const char* a3 = a2 + kstep; const char* b3 = b2 + kstep;
;             if constexpr (SP2) {
;             PG8_LDB(B0, 0, 0); PG8_LDB(B1, 0, 1); PG8_SCHED; PG8_LDA(At, 0, 0); PG8_STAGE(PG8_SA(1, 1), a1 + hstep, voffA);
;             PG8_WAIT_V(8); PG8_WAIT_L(0); PG8_BAR; PG8_MMA(0, 0, At, B0); PG8_MMA(0, 1, At, B1); PG8_BAR; PG8_SCHED;
;             PG8_LDA(At, 0, 1); PG8_STAGE(PG8_SB(0, 0), b2, voffB); PG8_STAGE(PG8_SB(0, 1), b2 + hstep, voffB); PG8_STAGE(PG8_SA(0, 0), a2, voffA);
;             PG8_WAIT_V(8); PG8_WAIT_L(0); PG8_BAR; PG8_MMA(1, 0, At, B0); PG8_MMA(1, 1, At, B1); PG8_BAR; PG8_SCHED;
.LBB0_305:
	s_ashr_i32 s9, s8, 31
	s_lshl_b64 s[12:13], s[8:9], 20
	s_add_u32 s12, s88, s12
	s_addc_u32 s13, s89, s13
	s_and_b64 s[14:15], s[10:11], exec
	s_cselect_b32 s9, s13, s17
	s_cselect_b32 s70, s12, s16
	s_ashr_i32 s7, s6, 31
	s_lshl_b64 s[14:15], s[6:7], 20
	s_add_u32 s14, s24, s14
	s_addc_u32 s15, s25, s15
	s_and_b64 s[22:23], s[10:11], exec
	s_cselect_b32 s7, s15, s21
	s_cselect_b32 s71, s14, s20
	s_add_u32 s16, s16, 0x80080
	s_addc_u32 s17, s17, 0
	s_add_u32 s72, s20, 0x100
	s_addc_u32 s73, s21, 0
	s_mov_b32 s74, -2
	s_add_u32 s20, s16, 0xfff80080
	s_addc_u32 s21, s17, -1
	s_add_i32 s58, 0, 0x10000
	s_cmp_eq_u32 s74, 28
	s_cselect_b32 s23, s9, s21
	s_cselect_b32 s22, s70, s20
	v_add_u32_e32 v144, s58, v147
	s_cselect_b32 s21, s7, s73
	s_cselect_b32 s20, s71, s72
	s_add_i32 s75, 0, 0x14000
	ds_read_b128 v[140:143], v144
	ds_read_b128 v[154:157], v144 offset:1024
	ds_read_b128 v[158:161], v144 offset:2048
	ds_read_b128 v[162:165], v144 offset:3072
	v_add_u32_e32 v144, s75, v147
	ds_read_b128 v[166:169], v144
	ds_read_b128 v[170:173], v144 offset:1024
	ds_read_b128 v[174:177], v144 offset:2048
	ds_read_b128 v[194:197], v144 offset:3072
	v_lshl_add_u64 v[150:151], s[16:17], 0, v[136:137]
	s_add_i32 m0, s27, 0xc000
	ds_read_b128 v[198:201], v153
	ds_read_b128 v[202:205], v153 offset:1024
	ds_read_b128 v[206:209], v153 offset:2048
	ds_read_b128 v[210:213], v153 offset:3072
	ds_read_b128 v[234:237], v153 offset:4096
	ds_read_b128 v[238:241], v153 offset:5120
	ds_read_b128 v[242:245], v153 offset:6144
	ds_read_b128 v[246:249], v153 offset:7168
	global_load_lds_dwordx4 v[150:151], off
	v_lshl_add_u64 v[150:151], s[16:17], 0, v[138:139]
	s_add_i32 m0, s27, 0xe000
	s_nop 0
	global_load_lds_dwordx4 v[150:151], off
	s_waitcnt vmcnt(8)
	s_waitcnt lgkmcnt(0)
	s_barrier
	s_setprio 1
	s_waitcnt lgkmcnt(0)
	v_mfma_f32_16x16x32_bf16 v[126:129], v[140:143], v[198:201], 0
	v_mfma_f32_16x16x32_bf16 v[122:125], v[158:161], v[198:201], 0
	v_mfma_f32_16x16x32_bf16 v[114:117], v[140:143], v[206:209], 0
	v_mfma_f32_16x16x32_bf16 v[106:109], v[158:161], v[206:209], 0
	v_mfma_f32_16x16x32_bf16 v[98:101], v[140:143], v[234:237], 0
	v_mfma_f32_16x16x32_bf16 v[90:93], v[158:161], v[234:237], 0
	v_mfma_f32_16x16x32_bf16 v[82:85], v[140:143], v[242:245], 0
	v_mfma_f32_16x16x32_bf16 v[74:77], v[158:161], v[242:245], 0
	v_mfma_f32_16x16x32_bf16 v[126:129], v[154:157], v[202:205], v[126:129]
	v_mfma_f32_16x16x32_bf16 v[122:125], v[162:165], v[202:205], v[122:125]
	v_mfma_f32_16x16x32_bf16 v[114:117], v[154:157], v[210:213], v[114:117]
	v_mfma_f32_16x16x32_bf16 v[106:109], v[162:165], v[210:213], v[106:109]
	v_mfma_f32_16x16x32_bf16 v[98:101], v[154:157], v[238:241], v[98:101]
	v_mfma_f32_16x16x32_bf16 v[90:93], v[162:165], v[238:241], v[90:93]
	v_mfma_f32_16x16x32_bf16 v[82:85], v[154:157], v[246:249], v[82:85]
	v_mfma_f32_16x16x32_bf16 v[74:77], v[162:165], v[246:249], v[74:77]
	s_setprio 0
	s_setprio 1
	v_mfma_f32_16x16x32_bf16 v[118:121], v[166:169], v[198:201], 0
	v_mfma_f32_16x16x32_bf16 v[110:113], v[174:177], v[198:201], 0
	v_mfma_f32_16x16x32_bf16 v[102:105], v[166:169], v[206:209], 0
	v_mfma_f32_16x16x32_bf16 v[94:97], v[174:177], v[206:209], 0
	v_mfma_f32_16x16x32_bf16 v[86:89], v[166:169], v[234:237], 0
	v_mfma_f32_16x16x32_bf16 v[78:81], v[174:177], v[234:237], 0
	v_mfma_f32_16x16x32_bf16 v[70:73], v[166:169], v[242:245], 0
	v_mfma_f32_16x16x32_bf16 v[66:69], v[174:177], v[242:245], 0
	v_mfma_f32_16x16x32_bf16 v[118:121], v[170:173], v[202:205], v[118:121]
	v_mfma_f32_16x16x32_bf16 v[110:113], v[194:197], v[202:205], v[110:113]
	v_mfma_f32_16x16x32_bf16 v[102:105], v[170:173], v[210:213], v[102:105]
	v_mfma_f32_16x16x32_bf16 v[94:97], v[194:197], v[210:213], v[94:97]
	v_mfma_f32_16x16x32_bf16 v[86:89], v[170:173], v[238:241], v[86:89]
	v_mfma_f32_16x16x32_bf16 v[78:81], v[194:197], v[238:241], v[78:81]
	v_mfma_f32_16x16x32_bf16 v[70:73], v[170:173], v[246:249], v[70:73]
	v_mfma_f32_16x16x32_bf16 v[66:69], v[194:197], v[246:249], v[66:69]
	s_setprio 0
	s_barrier
	s_add_i32 s58, s58, s26
	v_lshl_add_u64 v[150:151], s[20:21], 0, v[0:1]
	s_mov_b32 m0, s58
	ds_read_b128 v[198:201], v153 offset:16384
	ds_read_b128 v[202:205], v153 offset:17408
	ds_read_b128 v[206:209], v153 offset:18432
	ds_read_b128 v[210:213], v153 offset:19456
	ds_read_b128 v[234:237], v153 offset:20480
	ds_read_b128 v[238:241], v153 offset:21504
	ds_read_b128 v[242:245], v153 offset:22528
	ds_read_b128 v[246:249], v153 offset:23552
	global_load_lds_dwordx4 v[150:151], off
	s_add_i32 m0, s58, 0x2000
	s_add_u32 s58, s20, 0x80000
	v_lshl_add_u64 v[178:179], s[20:21], 0, v[130:131]
	s_addc_u32 s59, s21, 0
	s_add_i32 s75, s75, s26
	global_load_lds_dwordx4 v[178:179], off
	v_lshl_add_u64 v[214:215], s[58:59], 0, v[0:1]
	s_mov_b32 m0, s75
	v_lshl_add_u64 v[224:225], s[22:23], 0, v[132:133]
	global_load_lds_dwordx4 v[214:215], off
	v_lshl_add_u64 v[214:215], s[58:59], 0, v[130:131]
	s_add_i32 m0, s75, 0x2000
	s_nop 0
	global_load_lds_dwordx4 v[214:215], off
	v_lshl_add_u64 v[214:215], s[22:23], 0, v[134:135]
	s_mov_b32 m0, s27
	s_nop 0
	global_load_lds_dwordx4 v[214:215], off
	s_mov_b32 m0, s28
	s_nop 0
	global_load_lds_dwordx4 v[224:225], off
	s_waitcnt vmcnt(8)
	s_waitcnt lgkmcnt(0)
	s_barrier
; #define PG8_STAGE(bufoff, gbase, voff) do { _Pragma("unroll") for (int _i = 0; _i < 2; ++_i) \
;         __builtin_amdgcn_global_load_lds((const unsigned*)((const char*)(gbase) + (voff)[_i]), (LAS unsigned*)(lds + (bufoff) + ldsw + _i * 8192), 16, 0, 0); } while (0)
; #define PG8_LDA(dst, b, h) do { _Pragma("unroll") for (int m = 0; m < 4; ++m) _Pragma("unroll") for (int k = 0; k < 2; ++k) dst[m][k] = *(const LAS bf16x8*)(lds + PG8_SA(b, h) + aoff + m * 2048 + k * 1024); } while (0)
; #define PG8_LDB(dst, b, h) do { _Pragma("unroll") for (int n = 0; n < 2; ++n) _Pragma("unroll") for (int k = 0; k < 2; ++k) dst[n][k] = *(const LAS bf16x8*)(lds + PG8_SB(b, h) + boff + n * 2048 + k * 1024); } while (0)
; #define PG8_MMA(ai, bj, At, Bt) do { __builtin_amdgcn_s_setprio(1); _Pragma("unroll") for (int m = 0; m < 4; ++m) _Pragma("unroll") for (int n = 0; n < 2; ++n) _Pragma("unroll") for (int k = 0; k < 2; ++k) \
;         acc[ai][bj][m][n] = __builtin_amdgcn_mfma_f32_16x16x32_bf16(Bt[n][k], At[m][k], acc[ai][bj][m][n], 0, 0, 0); __builtin_amdgcn_s_setprio(0); } while (0)
; #define PG8_WAIT_V(n) asm volatile("s_waitcnt vmcnt(" #n ")" ::: "memory")
; #define PG8_WAIT_L(n) asm volatile("s_waitcnt lgkmcnt(" #n ")" ::: "memory")
; #define PG8_BAR __builtin_amdgcn_s_barrier()
; #define PG8_SCHED __builtin_amdgcn_sched_barrier(0)
; template <class Epi, class Sched, bool ALIGN_EPI = true, bool SP2 = true>
; __device__ __forceinline__ void gemm_phase(LAS unsigned char* lds, const Gemm g, const Sched& S, const Epi& E) {
;     ...
;             PG8_LDA(At, 0, 1); PG8_STAGE(PG8_SB(0, 0), b2, voffB); PG8_STAGE(PG8_SB(0, 1), b2 + hstep, voffB); PG8_STAGE(PG8_SA(0, 0), a2, voffA);
;             PG8_WAIT_V(8); PG8_WAIT_L(0); PG8_BAR; PG8_MMA(1, 0, At, B0); PG8_MMA(1, 1, At, B1); PG8_BAR; PG8_SCHED;
;             PG8_LDB(B0, 1, 0); PG8_LDB(B1, 1, 1); PG8_SCHED; PG8_LDA(At, 1, 0); PG8_STAGE(PG8_SA(0, 1), a2 + hstep, voffA);
;             PG8_WAIT_V(8); PG8_WAIT_L(0); PG8_BAR; PG8_MMA(0, 0, At, B0); PG8_MMA(0, 1, At, B1); PG8_BAR; PG8_SCHED;
	s_setprio 1
	s_waitcnt lgkmcnt(0)
	v_mfma_f32_16x16x32_bf16 v[62:65], v[140:143], v[198:201], 0
	v_mfma_f32_16x16x32_bf16 v[58:61], v[158:161], v[198:201], 0
	v_mfma_f32_16x16x32_bf16 v[50:53], v[140:143], v[206:209], 0
	v_mfma_f32_16x16x32_bf16 v[42:45], v[158:161], v[206:209], 0
	v_mfma_f32_16x16x32_bf16 v[34:37], v[140:143], v[234:237], 0
	v_mfma_f32_16x16x32_bf16 v[26:29], v[158:161], v[234:237], 0
	v_mfma_f32_16x16x32_bf16 v[18:21], v[140:143], v[242:245], 0
	v_mfma_f32_16x16x32_bf16 v[10:13], v[158:161], v[242:245], 0
	v_mfma_f32_16x16x32_bf16 v[62:65], v[154:157], v[202:205], v[62:65]
	v_mfma_f32_16x16x32_bf16 v[58:61], v[162:165], v[202:205], v[58:61]
	v_mfma_f32_16x16x32_bf16 v[50:53], v[154:157], v[210:213], v[50:53]
	v_mfma_f32_16x16x32_bf16 v[42:45], v[162:165], v[210:213], v[42:45]
	v_mfma_f32_16x16x32_bf16 v[34:37], v[154:157], v[238:241], v[34:37]
	v_mfma_f32_16x16x32_bf16 v[26:29], v[162:165], v[238:241], v[26:29]
	v_mfma_f32_16x16x32_bf16 v[18:21], v[154:157], v[246:249], v[18:21]
	v_mfma_f32_16x16x32_bf16 v[10:13], v[162:165], v[246:249], v[10:13]
	s_setprio 0
	s_setprio 1
	v_mfma_f32_16x16x32_bf16 v[54:57], v[166:169], v[198:201], 0
	v_mfma_f32_16x16x32_bf16 v[46:49], v[174:177], v[198:201], 0
	v_mfma_f32_16x16x32_bf16 v[38:41], v[166:169], v[206:209], 0
	v_mfma_f32_16x16x32_bf16 v[30:33], v[174:177], v[206:209], 0
	v_mfma_f32_16x16x32_bf16 v[22:25], v[166:169], v[234:237], 0
	v_mfma_f32_16x16x32_bf16 v[14:17], v[174:177], v[234:237], 0
	v_mfma_f32_16x16x32_bf16 v[6:9], v[166:169], v[242:245], 0
	v_mfma_f32_16x16x32_bf16 v[2:5], v[174:177], v[242:245], 0
	v_mfma_f32_16x16x32_bf16 v[54:57], v[170:173], v[202:205], v[54:57]
	v_mfma_f32_16x16x32_bf16 v[46:49], v[194:197], v[202:205], v[46:49]
	v_mfma_f32_16x16x32_bf16 v[38:41], v[170:173], v[210:213], v[38:41]
	v_mfma_f32_16x16x32_bf16 v[30:33], v[194:197], v[210:213], v[30:33]
	v_mfma_f32_16x16x32_bf16 v[22:25], v[170:173], v[238:241], v[22:25]
	v_mfma_f32_16x16x32_bf16 v[14:17], v[194:197], v[238:241], v[14:17]
	v_mfma_f32_16x16x32_bf16 v[6:9], v[170:173], v[246:249], v[6:9]
	v_mfma_f32_16x16x32_bf16 v[2:5], v[194:197], v[246:249], v[2:5]
	s_setprio 0
	s_barrier
	s_add_i32 s58, 0, 0x18000
	v_add_u32_e32 v144, s58, v147
	s_add_i32 s59, 0, 0x1c000
	ds_read_b128 v[140:143], v144
	ds_read_b128 v[154:157], v144 offset:1024
	ds_read_b128 v[158:161], v144 offset:2048
	ds_read_b128 v[162:165], v144 offset:3072
	v_add_u32_e32 v144, s59, v147
	ds_read_b128 v[166:169], v144
	ds_read_b128 v[170:173], v144 offset:1024
	ds_read_b128 v[174:177], v144 offset:2048
	ds_read_b128 v[194:197], v144 offset:3072
	s_add_u32 s22, s22, 0x80000
	s_addc_u32 s23, s23, 0
	s_mov_b32 m0, s29
	v_lshl_add_u64 v[250:251], s[22:23], 0, v[134:135]
	ds_read_b128 v[198:201], v153 offset:32768
	ds_read_b128 v[202:205], v153 offset:33792
	ds_read_b128 v[206:209], v153 offset:34816
	ds_read_b128 v[210:213], v153 offset:35840
	ds_read_b128 v[234:237], v153 offset:36864
	ds_read_b128 v[238:241], v153 offset:37888
	ds_read_b128 v[242:245], v153 offset:38912
	ds_read_b128 v[246:249], v153 offset:39936
	global_load_lds_dwordx4 v[250:251], off
	v_lshl_add_u64 v[250:251], s[22:23], 0, v[132:133]
	s_mov_b32 m0, s30
	s_nop 0
	global_load_lds_dwordx4 v[250:251], off
	s_waitcnt vmcnt(8)
	s_waitcnt lgkmcnt(0)
	s_barrier
	s_setprio 1
	s_waitcnt lgkmcnt(0)
	v_mfma_f32_16x16x32_bf16 v[126:129], v[140:143], v[198:201], v[126:129]
	v_mfma_f32_16x16x32_bf16 v[122:125], v[158:161], v[198:201], v[122:125]
	v_mfma_f32_16x16x32_bf16 v[114:117], v[140:143], v[206:209], v[114:117]
	v_mfma_f32_16x16x32_bf16 v[106:109], v[158:161], v[206:209], v[106:109]
	v_mfma_f32_16x16x32_bf16 v[98:101], v[140:143], v[234:237], v[98:101]
	v_mfma_f32_16x16x32_bf16 v[90:93], v[158:161], v[234:237], v[90:93]
	v_mfma_f32_16x16x32_bf16 v[82:85], v[140:143], v[242:245], v[82:85]
	v_mfma_f32_16x16x32_bf16 v[74:77], v[158:161], v[242:245], v[74:77]
	v_mfma_f32_16x16x32_bf16 v[126:129], v[154:157], v[202:205], v[126:129]
	v_mfma_f32_16x16x32_bf16 v[122:125], v[162:165], v[202:205], v[122:125]
	v_mfma_f32_16x16x32_bf16 v[114:117], v[154:157], v[210:213], v[114:117]
	v_mfma_f32_16x16x32_bf16 v[106:109], v[162:165], v[210:213], v[106:109]
	v_mfma_f32_16x16x32_bf16 v[98:101], v[154:157], v[238:241], v[98:101]
	v_mfma_f32_16x16x32_bf16 v[90:93], v[162:165], v[238:241], v[90:93]
	v_mfma_f32_16x16x32_bf16 v[82:85], v[154:157], v[246:249], v[82:85]
	v_mfma_f32_16x16x32_bf16 v[74:77], v[162:165], v[246:249], v[74:77]
	s_setprio 0
	s_setprio 1
	v_mfma_f32_16x16x32_bf16 v[118:121], v[166:169], v[198:201], v[118:121]
	v_mfma_f32_16x16x32_bf16 v[110:113], v[174:177], v[198:201], v[110:113]
	v_mfma_f32_16x16x32_bf16 v[102:105], v[166:169], v[206:209], v[102:105]
	v_mfma_f32_16x16x32_bf16 v[94:97], v[174:177], v[206:209], v[94:97]
	v_mfma_f32_16x16x32_bf16 v[86:89], v[166:169], v[234:237], v[86:89]
	v_mfma_f32_16x16x32_bf16 v[78:81], v[174:177], v[234:237], v[78:81]
	v_mfma_f32_16x16x32_bf16 v[70:73], v[166:169], v[242:245], v[70:73]
	v_mfma_f32_16x16x32_bf16 v[66:69], v[174:177], v[242:245], v[66:69]
	v_mfma_f32_16x16x32_bf16 v[118:121], v[170:173], v[202:205], v[118:121]
	v_mfma_f32_16x16x32_bf16 v[110:113], v[194:197], v[202:205], v[110:113]
	v_mfma_f32_16x16x32_bf16 v[102:105], v[170:173], v[210:213], v[102:105]
	v_mfma_f32_16x16x32_bf16 v[94:97], v[194:197], v[210:213], v[94:97]
	v_mfma_f32_16x16x32_bf16 v[86:89], v[170:173], v[238:241], v[86:89]
	v_mfma_f32_16x16x32_bf16 v[78:81], v[194:197], v[238:241], v[78:81]
	v_mfma_f32_16x16x32_bf16 v[70:73], v[170:173], v[246:249], v[70:73]
	v_mfma_f32_16x16x32_bf16 v[66:69], v[194:197], v[246:249], v[66:69]
	s_setprio 0
	s_barrier
; #define PG8_STAGE(bufoff, gbase, voff) do { _Pragma("unroll") for (int _i = 0; _i < 2; ++_i) \
;         __builtin_amdgcn_global_load_lds((const unsigned*)((const char*)(gbase) + (voff)[_i]), (LAS unsigned*)(lds + (bufoff) + ldsw + _i * 8192), 16, 0, 0); } while (0)
; #define PG8_LDA(dst, b, h) do { _Pragma("unroll") for (int m = 0; m < 4; ++m) _Pragma("unroll") for (int k = 0; k < 2; ++k) dst[m][k] = *(const LAS bf16x8*)(lds + PG8_SA(b, h) + aoff + m * 2048 + k * 1024); } while (0)
; #define PG8_MMA(ai, bj, At, Bt) do { __builtin_amdgcn_s_setprio(1); _Pragma("unroll") for (int m = 0; m < 4; ++m) _Pragma("unroll") for (int n = 0; n < 2; ++n) _Pragma("unroll") for (int k = 0; k < 2; ++k) \
;         acc[ai][bj][m][n] = __builtin_amdgcn_mfma_f32_16x16x32_bf16(Bt[n][k], At[m][k], acc[ai][bj][m][n], 0, 0, 0); __builtin_amdgcn_s_setprio(0); } while (0)
; #define PG8_WAIT_V(n) asm volatile("s_waitcnt vmcnt(" #n ")" ::: "memory")
; #define PG8_WAIT_L(n) asm volatile("s_waitcnt lgkmcnt(" #n ")" ::: "memory")
; #define PG8_BAR __builtin_amdgcn_s_barrier()
; #define PG8_SCHED __builtin_amdgcn_sched_barrier(0)
; template <class Epi, class Sched, bool ALIGN_EPI = true, bool SP2 = true>
; __device__ __forceinline__ void gemm_phase(LAS unsigned char* lds, const Gemm g, const Sched& S, const Epi& E) {
;     ...
;         for (int t = 0; t < nt; t += 2) {
;     ...
;             PG8_LDA(At, 1, 1); PG8_STAGE(PG8_SB(1, 0), b3, voffB); PG8_STAGE(PG8_SB(1, 1), b3 + hstep, voffB); PG8_STAGE(PG8_SA(1, 0), a3, voffA);
;             PG8_WAIT_V(8); PG8_WAIT_L(0); PG8_BAR; PG8_MMA(1, 0, At, B0); PG8_MMA(1, 1, At, B1); PG8_BAR; PG8_SCHED;
	s_add_i32 s22, s58, s26
	v_lshl_add_u64 v[150:151], v[150:151], 0, s[92:93]
	s_mov_b32 m0, s22
	ds_read_b128 v[198:201], v153 offset:49152
	ds_read_b128 v[202:205], v153 offset:50176
	ds_read_b128 v[206:209], v153 offset:51200
	ds_read_b128 v[210:213], v153 offset:52224
	ds_read_b128 v[234:237], v153 offset:53248
	ds_read_b128 v[238:241], v153 offset:54272
	ds_read_b128 v[242:245], v153 offset:55296
	ds_read_b128 v[246:249], v153 offset:56320
	global_load_lds_dwordx4 v[150:151], off
	s_add_i32 m0, s22, 0x2000
	s_add_u32 s20, s20, 0x80080
	v_lshl_add_u64 v[150:151], v[178:179], 0, s[92:93]
	s_addc_u32 s21, s21, 0
	s_add_i32 s22, s59, s26
	global_load_lds_dwordx4 v[150:151], off
	v_lshl_add_u64 v[150:151], s[20:21], 0, v[0:1]
	s_mov_b32 m0, s22
	s_nop 0
	global_load_lds_dwordx4 v[150:151], off
	v_lshl_add_u64 v[150:151], s[20:21], 0, v[130:131]
	s_add_i32 m0, s22, 0x2000
	s_nop 0
	global_load_lds_dwordx4 v[150:151], off
	v_lshl_add_u64 v[150:151], v[214:215], 0, s[92:93]
	s_mov_b32 m0, s31
	s_nop 0
	global_load_lds_dwordx4 v[150:151], off
	v_lshl_add_u64 v[150:151], v[224:225], 0, s[92:93]
	s_mov_b32 m0, s34
	s_nop 0
	global_load_lds_dwordx4 v[150:151], off
	s_waitcnt vmcnt(8)
	s_waitcnt lgkmcnt(0)
	s_barrier
	s_setprio 1
	s_waitcnt lgkmcnt(0)
	v_mfma_f32_16x16x32_bf16 v[62:65], v[140:143], v[198:201], v[62:65]
	v_mfma_f32_16x16x32_bf16 v[58:61], v[158:161], v[198:201], v[58:61]
	v_mfma_f32_16x16x32_bf16 v[50:53], v[140:143], v[206:209], v[50:53]
	v_mfma_f32_16x16x32_bf16 v[42:45], v[158:161], v[206:209], v[42:45]
	v_mfma_f32_16x16x32_bf16 v[34:37], v[140:143], v[234:237], v[34:37]
	v_mfma_f32_16x16x32_bf16 v[26:29], v[158:161], v[234:237], v[26:29]
	v_mfma_f32_16x16x32_bf16 v[18:21], v[140:143], v[242:245], v[18:21]
	v_mfma_f32_16x16x32_bf16 v[10:13], v[158:161], v[242:245], v[10:13]
	v_mfma_f32_16x16x32_bf16 v[62:65], v[154:157], v[202:205], v[62:65]
	v_mfma_f32_16x16x32_bf16 v[58:61], v[162:165], v[202:205], v[58:61]
	v_mfma_f32_16x16x32_bf16 v[50:53], v[154:157], v[210:213], v[50:53]
	v_mfma_f32_16x16x32_bf16 v[42:45], v[162:165], v[210:213], v[42:45]
	v_mfma_f32_16x16x32_bf16 v[34:37], v[154:157], v[238:241], v[34:37]
	v_mfma_f32_16x16x32_bf16 v[26:29], v[162:165], v[238:241], v[26:29]
	v_mfma_f32_16x16x32_bf16 v[18:21], v[154:157], v[246:249], v[18:21]
	v_mfma_f32_16x16x32_bf16 v[10:13], v[162:165], v[246:249], v[10:13]
	s_setprio 0
	s_setprio 1
	v_mfma_f32_16x16x32_bf16 v[54:57], v[166:169], v[198:201], v[54:57]
	v_mfma_f32_16x16x32_bf16 v[46:49], v[174:177], v[198:201], v[46:49]
	v_mfma_f32_16x16x32_bf16 v[38:41], v[166:169], v[206:209], v[38:41]
	v_mfma_f32_16x16x32_bf16 v[30:33], v[174:177], v[206:209], v[30:33]
	v_mfma_f32_16x16x32_bf16 v[22:25], v[166:169], v[234:237], v[22:25]
	v_mfma_f32_16x16x32_bf16 v[14:17], v[174:177], v[234:237], v[14:17]
	v_mfma_f32_16x16x32_bf16 v[6:9], v[166:169], v[242:245], v[6:9]
	v_mfma_f32_16x16x32_bf16 v[2:5], v[174:177], v[242:245], v[2:5]
	v_mfma_f32_16x16x32_bf16 v[54:57], v[170:173], v[202:205], v[54:57]
	v_mfma_f32_16x16x32_bf16 v[46:49], v[194:197], v[202:205], v[46:49]
	v_mfma_f32_16x16x32_bf16 v[38:41], v[170:173], v[210:213], v[38:41]
	v_mfma_f32_16x16x32_bf16 v[30:33], v[194:197], v[210:213], v[30:33]
	v_mfma_f32_16x16x32_bf16 v[22:25], v[170:173], v[238:241], v[22:25]
	v_mfma_f32_16x16x32_bf16 v[14:17], v[194:197], v[238:241], v[14:17]
	v_mfma_f32_16x16x32_bf16 v[6:9], v[170:173], v[246:249], v[6:9]
	v_mfma_f32_16x16x32_bf16 v[2:5], v[194:197], v[246:249], v[2:5]
	s_setprio 0
	s_barrier
	s_add_i32 s74, s74, 2
	s_add_u32 s16, s16, 0x100
	s_addc_u32 s17, s17, 0
	s_add_u32 s72, s72, 0x100
	s_addc_u32 s73, s73, 0
	s_cmp_gt_u32 s74, 29

;     __device__ bool next(int i, Unit& u) const { if (!so.next(i >> 1, u)) return false; u.kind = i & 1; return true; }
; #define PG8_STAGE(bufoff, gbase, voff) do { _Pragma("unroll") for (int _i = 0; _i < 2; ++_i) \
;         __builtin_amdgcn_global_load_lds((const unsigned*)((const char*)(gbase) + (voff)[_i]), (LAS unsigned*)(lds + (bufoff) + ldsw + _i * 8192), 16, 0, 0); } while (0)
; #define PG8_LDA(dst, b, h) do { _Pragma("unroll") for (int m = 0; m < 4; ++m) _Pragma("unroll") for (int k = 0; k < 2; ++k) dst[m][k] = *(const LAS bf16x8*)(lds + PG8_SA(b, h) + aoff + m * 2048 + k * 1024); } while (0)
; #define PG8_LDB(dst, b, h) do { _Pragma("unroll") for (int n = 0; n < 2; ++n) _Pragma("unroll") for (int k = 0; k < 2; ++k) dst[n][k] = *(const LAS bf16x8*)(lds + PG8_SB(b, h) + boff + n * 2048 + k * 1024); } while (0)
; #define PG8_WAIT_V(n) asm volatile("s_waitcnt vmcnt(" #n ")" ::: "memory")
; #define PG8_WAIT_L(n) asm volatile("s_waitcnt lgkmcnt(" #n ")" ::: "memory")
; #define PG8_BAR __builtin_amdgcn_s_barrier()
; template <class Epi, class Sched, bool ALIGN_EPI = true, bool SP2 = true>
; __device__ __forceinline__ void gemm_phase(LAS unsigned char* lds, const Gemm g, const Sched& S, const Epi& E) {
;     ...
;         const bool has_next = S.next(ui + 1, nxt);
;         const char* nA = has_next ? (const char*)(nxt.kind ? g.A1 : g.A0) + (size_t)nxt.pm * tstep : cA; const char* nB = has_next ? (const char*)(nxt.kind ? g.B1 : g.B0) + (size_t)nxt.pn * tstep : cB;
;         for (int t = 0; t < nt; t += 2) {
;             const bool last = (t == nt - 2);
;             const char* a1 = cA + (size_t)(t + 1) * kstep;
;             const char* a2 = last ? nA : cA + (size_t)(t + 2) * kstep; const char* b2 = last ? nB : cB + (size_t)(t + 2) * kstep;
;             const char* a3 = a2 + kstep; const char* b3 = b2 + kstep;
;             if constexpr (SP2) {
;             PG8_LDB(B0, 0, 0); PG8_LDB(B1, 0, 1); PG8_SCHED; PG8_LDA(At, 0, 0); PG8_STAGE(PG8_SA(1, 1), a1 + hstep, voffA);
;             PG8_WAIT_V(8); PG8_WAIT_L(0); PG8_BAR; PG8_MMA(0, 0, At, B0); PG8_MMA(0, 1, At, B1); PG8_BAR; PG8_SCHED;
;             PG8_LDA(At, 0, 1); PG8_STAGE(PG8_SB(0, 0), b2, voffB); PG8_STAGE(PG8_SB(0, 1), b2 + hstep, voffB); PG8_STAGE(PG8_SA(0, 0), a2, voffA);
;             PG8_WAIT_V(8); PG8_WAIT_L(0); PG8_BAR; PG8_MMA(1, 0, At, B0); PG8_MMA(1, 1, At, B1); PG8_BAR; PG8_SCHED;
.LBB0_786:
	s_ashr_i32 s15, s14, 31
	s_lshl_b64 s[16:17], s[14:15], 20
	s_add_u32 s16, s94, s16
	s_addc_u32 s17, s95, s17
	s_and_b64 s[18:19], s[12:13], exec
	s_cselect_b32 s15, s17, s21
	s_cselect_b32 s72, s16, s20
	s_ashr_i32 s9, s8, 31
	s_lshl_b64 s[18:19], s[8:9], 20
	s_add_u32 s18, s28, s18
	s_addc_u32 s19, s29, s19
	s_and_b64 s[24:25], s[12:13], exec
	s_cselect_b32 s9, s19, s23
	s_cselect_b32 s73, s18, s22
	s_add_u32 s76, s22, 0x100
	s_addc_u32 s77, s23, 0
	s_mov_b32 s78, -2
	s_waitcnt lgkmcnt(0)
	s_add_u32 s22, s20, 0x100
	s_addc_u32 s23, s21, 0
	s_add_i32 s58, 0, 0x10000
	s_cmp_eq_u32 s78, 28
	s_cselect_b32 s27, s15, s23
	s_cselect_b32 s26, s72, s22
	s_cselect_b32 s25, s9, s77
	s_cselect_b32 s24, s73, s76
	s_add_i32 s59, 0, 0x14000
	v_add_u32_e32 v148, s58, v179
	v_add_u32_e32 v164, s59, v179
	ds_read_b128 v[136:139], v148
	ds_read_b128 v[140:143], v148 offset:1024
	ds_read_b128 v[144:147], v148 offset:2048
	ds_read_b128 v[148:151], v148 offset:3072
	ds_read_b128 v[152:155], v164
	ds_read_b128 v[156:159], v164 offset:1024
	ds_read_b128 v[160:163], v164 offset:2048
	ds_read_b128 v[164:167], v164 offset:3072
	v_lshl_add_u64 v[176:177], s[20:21], 0, v[132:133]
	s_add_i32 m0, s31, 0xc000
	ds_read_b128 v[168:171], v194
	ds_read_b128 v[172:175], v194 offset:1024
	ds_read_b128 v[196:199], v194 offset:2048
	ds_read_b128 v[200:203], v194 offset:3072
	ds_read_b128 v[204:207], v194 offset:4096
	ds_read_b128 v[208:211], v194 offset:5120
	ds_read_b128 v[212:215], v194 offset:6144
	ds_read_b128 v[234:237], v194 offset:7168
	global_load_lds_dwordx4 v[176:177], off
	v_lshl_add_u64 v[176:177], s[20:21], 0, v[134:135]
	s_add_i32 m0, s31, 0xe000
	s_nop 0
	global_load_lds_dwordx4 v[176:177], off
	s_waitcnt vmcnt(8)
	s_waitcnt lgkmcnt(0)
	s_barrier
	s_setprio 1
	s_waitcnt lgkmcnt(0)
	v_mfma_f32_16x16x32_bf16 v[126:129], v[136:139], v[168:171], 0
	v_mfma_f32_16x16x32_bf16 v[122:125], v[144:147], v[168:171], 0
	v_mfma_f32_16x16x32_bf16 v[110:113], v[136:139], v[196:199], 0
	v_mfma_f32_16x16x32_bf16 v[106:109], v[144:147], v[196:199], 0
	v_mfma_f32_16x16x32_bf16 v[94:97], v[136:139], v[204:207], 0
	v_mfma_f32_16x16x32_bf16 v[90:93], v[144:147], v[204:207], 0
	v_mfma_f32_16x16x32_bf16 v[78:81], v[136:139], v[212:215], 0
	v_mfma_f32_16x16x32_bf16 v[74:77], v[144:147], v[212:215], 0
	v_mfma_f32_16x16x32_bf16 v[126:129], v[140:143], v[172:175], v[126:129]
	v_mfma_f32_16x16x32_bf16 v[122:125], v[148:151], v[172:175], v[122:125]
	v_mfma_f32_16x16x32_bf16 v[110:113], v[140:143], v[200:203], v[110:113]
	v_mfma_f32_16x16x32_bf16 v[106:109], v[148:151], v[200:203], v[106:109]
	v_mfma_f32_16x16x32_bf16 v[94:97], v[140:143], v[208:211], v[94:97]
	v_mfma_f32_16x16x32_bf16 v[90:93], v[148:151], v[208:211], v[90:93]
	v_mfma_f32_16x16x32_bf16 v[78:81], v[140:143], v[234:237], v[78:81]
	v_mfma_f32_16x16x32_bf16 v[74:77], v[148:151], v[234:237], v[74:77]
	s_setprio 0
	s_setprio 1
	v_mfma_f32_16x16x32_bf16 v[118:121], v[152:155], v[168:171], 0
	v_mfma_f32_16x16x32_bf16 v[114:117], v[160:163], v[168:171], 0
	v_mfma_f32_16x16x32_bf16 v[102:105], v[152:155], v[196:199], 0
	v_mfma_f32_16x16x32_bf16 v[98:101], v[160:163], v[196:199], 0
	v_mfma_f32_16x16x32_bf16 v[86:89], v[152:155], v[204:207], 0
	v_mfma_f32_16x16x32_bf16 v[82:85], v[160:163], v[204:207], 0
	v_mfma_f32_16x16x32_bf16 v[70:73], v[152:155], v[212:215], 0
	v_mfma_f32_16x16x32_bf16 v[66:69], v[160:163], v[212:215], 0
	v_mfma_f32_16x16x32_bf16 v[118:121], v[156:159], v[172:175], v[118:121]
	v_mfma_f32_16x16x32_bf16 v[114:117], v[164:167], v[172:175], v[114:117]
	v_mfma_f32_16x16x32_bf16 v[102:105], v[156:159], v[200:203], v[102:105]
	v_mfma_f32_16x16x32_bf16 v[98:101], v[164:167], v[200:203], v[98:101]
	v_mfma_f32_16x16x32_bf16 v[86:89], v[156:159], v[208:211], v[86:89]
	v_mfma_f32_16x16x32_bf16 v[82:85], v[164:167], v[208:211], v[82:85]
	v_mfma_f32_16x16x32_bf16 v[70:73], v[156:159], v[234:237], v[70:73]
	v_mfma_f32_16x16x32_bf16 v[66:69], v[164:167], v[234:237], v[66:69]
	s_setprio 0
	s_barrier
	s_add_i32 s20, s58, s30
	v_lshl_add_u64 v[176:177], s[24:25], 0, v[0:1]
	s_mov_b32 m0, s20
	ds_read_b128 v[168:171], v194 offset:16384
	ds_read_b128 v[172:175], v194 offset:17408
	ds_read_b128 v[196:199], v194 offset:18432
	ds_read_b128 v[200:203], v194 offset:19456
	ds_read_b128 v[204:207], v194 offset:20480
	ds_read_b128 v[208:211], v194 offset:21504
	ds_read_b128 v[212:215], v194 offset:22528
	ds_read_b128 v[234:237], v194 offset:23552
	global_load_lds_dwordx4 v[176:177], off
	s_add_i32 m0, s20, 0x2000
	s_add_u32 s20, s24, 0x80000
	v_lshl_add_u64 v[224:225], s[24:25], 0, v[130:131]
	s_addc_u32 s21, s25, 0
	s_add_i32 s58, s59, s30
	global_load_lds_dwordx4 v[224:225], off
	v_lshl_add_u64 v[238:239], s[20:21], 0, v[0:1]
	s_mov_b32 m0, s58
	v_lshl_add_u64 v[240:241], s[26:27], 0, v[130:131]
	global_load_lds_dwordx4 v[238:239], off
	v_lshl_add_u64 v[238:239], s[20:21], 0, v[130:131]
	s_add_i32 m0, s58, 0x2000
	s_nop 0
	global_load_lds_dwordx4 v[238:239], off
	v_lshl_add_u64 v[238:239], s[26:27], 0, v[0:1]
	s_mov_b32 m0, s31
	s_nop 0
	global_load_lds_dwordx4 v[238:239], off
	s_mov_b32 m0, s34
	s_nop 0
	global_load_lds_dwordx4 v[240:241], off
	s_waitcnt vmcnt(8)
	s_waitcnt lgkmcnt(0)
	s_barrier
; #define PG8_STAGE(bufoff, gbase, voff) do { _Pragma("unroll") for (int _i = 0; _i < 2; ++_i) \
;         __builtin_amdgcn_global_load_lds((const unsigned*)((const char*)(gbase) + (voff)[_i]), (LAS unsigned*)(lds + (bufoff) + ldsw + _i * 8192), 16, 0, 0); } while (0)
; #define PG8_LDA(dst, b, h) do { _Pragma("unroll") for (int m = 0; m < 4; ++m) _Pragma("unroll") for (int k = 0; k < 2; ++k) dst[m][k] = *(const LAS bf16x8*)(lds + PG8_SA(b, h) + aoff + m * 2048 + k * 1024); } while (0)
; #define PG8_LDB(dst, b, h) do { _Pragma("unroll") for (int n = 0; n < 2; ++n) _Pragma("unroll") for (int k = 0; k < 2; ++k) dst[n][k] = *(const LAS bf16x8*)(lds + PG8_SB(b, h) + boff + n * 2048 + k * 1024); } while (0)
; #define PG8_MMA(ai, bj, At, Bt) do { __builtin_amdgcn_s_setprio(1); _Pragma("unroll") for (int m = 0; m < 4; ++m) _Pragma("unroll") for (int n = 0; n < 2; ++n) _Pragma("unroll") for (int k = 0; k < 2; ++k) \
;         acc[ai][bj][m][n] = __builtin_amdgcn_mfma_f32_16x16x32_bf16(Bt[n][k], At[m][k], acc[ai][bj][m][n], 0, 0, 0); __builtin_amdgcn_s_setprio(0); } while (0)
; #define PG8_WAIT_V(n) asm volatile("s_waitcnt vmcnt(" #n ")" ::: "memory")
; #define PG8_WAIT_L(n) asm volatile("s_waitcnt lgkmcnt(" #n ")" ::: "memory")
; #define PG8_BAR __builtin_amdgcn_s_barrier()
; #define PG8_SCHED __builtin_amdgcn_sched_barrier(0)
; template <class Epi, class Sched, bool ALIGN_EPI = true, bool SP2 = true>
; __device__ __forceinline__ void gemm_phase(LAS unsigned char* lds, const Gemm g, const Sched& S, const Epi& E) {
;     ...
;             PG8_WAIT_V(8); PG8_WAIT_L(0); PG8_BAR; PG8_MMA(1, 0, At, B0); PG8_MMA(1, 1, At, B1); PG8_BAR; PG8_SCHED;
;             PG8_LDB(B0, 1, 0); PG8_LDB(B1, 1, 1); PG8_SCHED; PG8_LDA(At, 1, 0); PG8_STAGE(PG8_SA(0, 1), a2 + hstep, voffA);
;             PG8_WAIT_V(8); PG8_WAIT_L(0); PG8_BAR; PG8_MMA(0, 0, At, B0); PG8_MMA(0, 1, At, B1); PG8_BAR; PG8_SCHED;
;             PG8_LDA(At, 1, 1); PG8_STAGE(PG8_SB(1, 0), b3, voffB); PG8_STAGE(PG8_SB(1, 1), b3 + hstep, voffB); PG8_STAGE(PG8_SA(1, 0), a3, voffA);
;             PG8_WAIT_V(8); PG8_WAIT_L(0); PG8_BAR; PG8_MMA(1, 0, At, B0); PG8_MMA(1, 1, At, B1); PG8_BAR; PG8_SCHED;
	s_setprio 1
	s_waitcnt lgkmcnt(0)
	v_mfma_f32_16x16x32_bf16 v[62:65], v[136:139], v[168:171], 0
	v_mfma_f32_16x16x32_bf16 v[58:61], v[144:147], v[168:171], 0
	v_mfma_f32_16x16x32_bf16 v[46:49], v[136:139], v[196:199], 0
	v_mfma_f32_16x16x32_bf16 v[42:45], v[144:147], v[196:199], 0
	v_mfma_f32_16x16x32_bf16 v[30:33], v[136:139], v[204:207], 0
	v_mfma_f32_16x16x32_bf16 v[26:29], v[144:147], v[204:207], 0
	v_mfma_f32_16x16x32_bf16 v[14:17], v[136:139], v[212:215], 0
	v_mfma_f32_16x16x32_bf16 v[10:13], v[144:147], v[212:215], 0
	v_mfma_f32_16x16x32_bf16 v[62:65], v[140:143], v[172:175], v[62:65]
	v_mfma_f32_16x16x32_bf16 v[58:61], v[148:151], v[172:175], v[58:61]
	v_mfma_f32_16x16x32_bf16 v[46:49], v[140:143], v[200:203], v[46:49]
	v_mfma_f32_16x16x32_bf16 v[42:45], v[148:151], v[200:203], v[42:45]
	v_mfma_f32_16x16x32_bf16 v[30:33], v[140:143], v[208:211], v[30:33]
	v_mfma_f32_16x16x32_bf16 v[26:29], v[148:151], v[208:211], v[26:29]
	v_mfma_f32_16x16x32_bf16 v[14:17], v[140:143], v[234:237], v[14:17]
	v_mfma_f32_16x16x32_bf16 v[10:13], v[148:151], v[234:237], v[10:13]
	s_setprio 0
	s_setprio 1
	v_mfma_f32_16x16x32_bf16 v[54:57], v[152:155], v[168:171], 0
	v_mfma_f32_16x16x32_bf16 v[50:53], v[160:163], v[168:171], 0
	v_mfma_f32_16x16x32_bf16 v[38:41], v[152:155], v[196:199], 0
	v_mfma_f32_16x16x32_bf16 v[34:37], v[160:163], v[196:199], 0
	v_mfma_f32_16x16x32_bf16 v[22:25], v[152:155], v[204:207], 0
	v_mfma_f32_16x16x32_bf16 v[18:21], v[160:163], v[204:207], 0
	v_mfma_f32_16x16x32_bf16 v[6:9], v[152:155], v[212:215], 0
	v_mfma_f32_16x16x32_bf16 v[2:5], v[160:163], v[212:215], 0
	v_mfma_f32_16x16x32_bf16 v[54:57], v[156:159], v[172:175], v[54:57]
	v_mfma_f32_16x16x32_bf16 v[50:53], v[164:167], v[172:175], v[50:53]
	v_mfma_f32_16x16x32_bf16 v[38:41], v[156:159], v[200:203], v[38:41]
	v_mfma_f32_16x16x32_bf16 v[34:37], v[164:167], v[200:203], v[34:37]
	v_mfma_f32_16x16x32_bf16 v[22:25], v[156:159], v[208:211], v[22:25]
	v_mfma_f32_16x16x32_bf16 v[18:21], v[164:167], v[208:211], v[18:21]
	v_mfma_f32_16x16x32_bf16 v[6:9], v[156:159], v[234:237], v[6:9]
	v_mfma_f32_16x16x32_bf16 v[2:5], v[164:167], v[234:237], v[2:5]
	s_setprio 0
	s_barrier
	s_add_i32 s58, 0, 0x18000
	s_add_i32 s59, 0, 0x1c000
	v_add_u32_e32 v148, s58, v179
	v_add_u32_e32 v164, s59, v179
	ds_read_b128 v[136:139], v148
	ds_read_b128 v[140:143], v148 offset:1024
	ds_read_b128 v[144:147], v148 offset:2048
	ds_read_b128 v[148:151], v148 offset:3072
	ds_read_b128 v[152:155], v164
	ds_read_b128 v[156:159], v164 offset:1024
	ds_read_b128 v[160:163], v164 offset:2048
	ds_read_b128 v[164:167], v164 offset:3072
	s_add_u32 s20, s26, 0x80000
	s_addc_u32 s21, s27, 0
	s_mov_b32 m0, s35
	v_lshl_add_u64 v[242:243], s[20:21], 0, v[0:1]
	ds_read_b128 v[168:171], v194 offset:32768
	ds_read_b128 v[172:175], v194 offset:33792
	ds_read_b128 v[196:199], v194 offset:34816
	ds_read_b128 v[200:203], v194 offset:35840
	ds_read_b128 v[204:207], v194 offset:36864
	ds_read_b128 v[208:211], v194 offset:37888
	ds_read_b128 v[212:215], v194 offset:38912
	ds_read_b128 v[234:237], v194 offset:39936
	global_load_lds_dwordx4 v[242:243], off
	v_lshl_add_u64 v[242:243], s[20:21], 0, v[130:131]
	s_mov_b32 m0, s70
	s_nop 0
	global_load_lds_dwordx4 v[242:243], off
	s_waitcnt vmcnt(8)
	s_waitcnt lgkmcnt(0)
	s_barrier
	s_setprio 1
	s_waitcnt lgkmcnt(0)
	v_mfma_f32_16x16x32_bf16 v[126:129], v[136:139], v[168:171], v[126:129]
	v_mfma_f32_16x16x32_bf16 v[122:125], v[144:147], v[168:171], v[122:125]
	v_mfma_f32_16x16x32_bf16 v[110:113], v[136:139], v[196:199], v[110:113]
	v_mfma_f32_16x16x32_bf16 v[106:109], v[144:147], v[196:199], v[106:109]
	v_mfma_f32_16x16x32_bf16 v[94:97], v[136:139], v[204:207], v[94:97]
	v_mfma_f32_16x16x32_bf16 v[90:93], v[144:147], v[204:207], v[90:93]
	v_mfma_f32_16x16x32_bf16 v[78:81], v[136:139], v[212:215], v[78:81]
	v_mfma_f32_16x16x32_bf16 v[74:77], v[144:147], v[212:215], v[74:77]
	v_mfma_f32_16x16x32_bf16 v[126:129], v[140:143], v[172:175], v[126:129]
	v_mfma_f32_16x16x32_bf16 v[122:125], v[148:151], v[172:175], v[122:125]
	v_mfma_f32_16x16x32_bf16 v[110:113], v[140:143], v[200:203], v[110:113]
	v_mfma_f32_16x16x32_bf16 v[106:109], v[148:151], v[200:203], v[106:109]
	v_mfma_f32_16x16x32_bf16 v[94:97], v[140:143], v[208:211], v[94:97]
	v_mfma_f32_16x16x32_bf16 v[90:93], v[148:151], v[208:211], v[90:93]
	v_mfma_f32_16x16x32_bf16 v[78:81], v[140:143], v[234:237], v[78:81]
	v_mfma_f32_16x16x32_bf16 v[74:77], v[148:151], v[234:237], v[74:77]
	s_setprio 0
	s_setprio 1
	v_mfma_f32_16x16x32_bf16 v[118:121], v[152:155], v[168:171], v[118:121]
	v_mfma_f32_16x16x32_bf16 v[114:117], v[160:163], v[168:171], v[114:117]
	v_mfma_f32_16x16x32_bf16 v[102:105], v[152:155], v[196:199], v[102:105]
	v_mfma_f32_16x16x32_bf16 v[98:101], v[160:163], v[196:199], v[98:101]
	v_mfma_f32_16x16x32_bf16 v[86:89], v[152:155], v[204:207], v[86:89]
	v_mfma_f32_16x16x32_bf16 v[82:85], v[160:163], v[204:207], v[82:85]
	v_mfma_f32_16x16x32_bf16 v[70:73], v[152:155], v[212:215], v[70:73]
	v_mfma_f32_16x16x32_bf16 v[66:69], v[160:163], v[212:215], v[66:69]
	v_mfma_f32_16x16x32_bf16 v[118:121], v[156:159], v[172:175], v[118:121]
	v_mfma_f32_16x16x32_bf16 v[114:117], v[164:167], v[172:175], v[114:117]
	v_mfma_f32_16x16x32_bf16 v[102:105], v[156:159], v[200:203], v[102:105]
	v_mfma_f32_16x16x32_bf16 v[98:101], v[164:167], v[200:203], v[98:101]
	v_mfma_f32_16x16x32_bf16 v[86:89], v[156:159], v[208:211], v[86:89]
	v_mfma_f32_16x16x32_bf16 v[82:85], v[164:167], v[208:211], v[82:85]
	v_mfma_f32_16x16x32_bf16 v[70:73], v[156:159], v[234:237], v[70:73]
	v_mfma_f32_16x16x32_bf16 v[66:69], v[164:167], v[234:237], v[66:69]
	s_setprio 0
	s_barrier
; #define PG8_STAGE(bufoff, gbase, voff) do { _Pragma("unroll") for (int _i = 0; _i < 2; ++_i) \
;         __builtin_amdgcn_global_load_lds((const unsigned*)((const char*)(gbase) + (voff)[_i]), (LAS unsigned*)(lds + (bufoff) + ldsw + _i * 8192), 16, 0, 0); } while (0)
; #define PG8_LDA(dst, b, h) do { _Pragma("unroll") for (int m = 0; m < 4; ++m) _Pragma("unroll") for (int k = 0; k < 2; ++k) dst[m][k] = *(const LAS bf16x8*)(lds + PG8_SA(b, h) + aoff + m * 2048 + k * 1024); } while (0)
; #define PG8_MMA(ai, bj, At, Bt) do { __builtin_amdgcn_s_setprio(1); _Pragma("unroll") for (int m = 0; m < 4; ++m) _Pragma("unroll") for (int n = 0; n < 2; ++n) _Pragma("unroll") for (int k = 0; k < 2; ++k) \
;         acc[ai][bj][m][n] = __builtin_amdgcn_mfma_f32_16x16x32_bf16(Bt[n][k], At[m][k], acc[ai][bj][m][n], 0, 0, 0); __builtin_amdgcn_s_setprio(0); } while (0)
; #define PG8_WAIT_V(n) asm volatile("s_waitcnt vmcnt(" #n ")" ::: "memory")
; #define PG8_WAIT_L(n) asm volatile("s_waitcnt lgkmcnt(" #n ")" ::: "memory")
; #define PG8_BAR __builtin_amdgcn_s_barrier()
; #define PG8_SCHED __builtin_amdgcn_sched_barrier(0)
; template <class Epi, class Sched, bool ALIGN_EPI = true, bool SP2 = true>
; __device__ __forceinline__ void gemm_phase(LAS unsigned char* lds, const Gemm g, const Sched& S, const Epi& E) {
;     ...
;             PG8_LDA(At, 1, 1); PG8_STAGE(PG8_SB(1, 0), b3, voffB); PG8_STAGE(PG8_SB(1, 1), b3 + hstep, voffB); PG8_STAGE(PG8_SA(1, 0), a3, voffA);
;             PG8_WAIT_V(8); PG8_WAIT_L(0); PG8_BAR; PG8_MMA(1, 0, At, B0); PG8_MMA(1, 1, At, B1); PG8_BAR; PG8_SCHED;
	s_add_i32 s20, s58, s30
	v_lshl_add_u64 v[176:177], v[176:177], 0, s[92:93]
	s_mov_b32 m0, s20
	ds_read_b128 v[168:171], v194 offset:49152
	ds_read_b128 v[172:175], v194 offset:50176
	ds_read_b128 v[196:199], v194 offset:51200
	ds_read_b128 v[200:203], v194 offset:52224
	ds_read_b128 v[204:207], v194 offset:53248
	ds_read_b128 v[208:211], v194 offset:54272
	ds_read_b128 v[212:215], v194 offset:55296
	ds_read_b128 v[234:237], v194 offset:56320
	global_load_lds_dwordx4 v[176:177], off
	s_add_i32 m0, s20, 0x2000
	s_add_u32 s20, s24, 0x80080
	v_lshl_add_u64 v[176:177], v[224:225], 0, s[92:93]
	s_addc_u32 s21, s25, 0
	s_add_i32 s24, s59, s30
	global_load_lds_dwordx4 v[176:177], off
	v_lshl_add_u64 v[176:177], s[20:21], 0, v[0:1]
	s_mov_b32 m0, s24
	s_nop 0
	global_load_lds_dwordx4 v[176:177], off
	v_lshl_add_u64 v[176:177], s[20:21], 0, v[130:131]
	s_add_i32 m0, s24, 0x2000
	s_nop 0
	global_load_lds_dwordx4 v[176:177], off
	v_lshl_add_u64 v[176:177], v[238:239], 0, s[92:93]
	s_mov_b32 m0, s71
	s_nop 0
	global_load_lds_dwordx4 v[176:177], off
	v_lshl_add_u64 v[176:177], v[240:241], 0, s[92:93]
	s_mov_b32 m0, s74
	s_nop 0
	global_load_lds_dwordx4 v[176:177], off
	s_waitcnt vmcnt(8)
	s_waitcnt lgkmcnt(0)
	s_barrier
	s_setprio 1
	s_waitcnt lgkmcnt(0)
	v_mfma_f32_16x16x32_bf16 v[62:65], v[136:139], v[168:171], v[62:65]
	v_mfma_f32_16x16x32_bf16 v[58:61], v[144:147], v[168:171], v[58:61]
	v_mfma_f32_16x16x32_bf16 v[46:49], v[136:139], v[196:199], v[46:49]
	v_mfma_f32_16x16x32_bf16 v[42:45], v[144:147], v[196:199], v[42:45]
	v_mfma_f32_16x16x32_bf16 v[30:33], v[136:139], v[204:207], v[30:33]
	v_mfma_f32_16x16x32_bf16 v[26:29], v[144:147], v[204:207], v[26:29]
	v_mfma_f32_16x16x32_bf16 v[14:17], v[136:139], v[212:215], v[14:17]
	v_mfma_f32_16x16x32_bf16 v[10:13], v[144:147], v[212:215], v[10:13]
	v_mfma_f32_16x16x32_bf16 v[62:65], v[140:143], v[172:175], v[62:65]
	v_mfma_f32_16x16x32_bf16 v[58:61], v[148:151], v[172:175], v[58:61]
	v_mfma_f32_16x16x32_bf16 v[46:49], v[140:143], v[200:203], v[46:49]
	v_mfma_f32_16x16x32_bf16 v[42:45], v[148:151], v[200:203], v[42:45]
	v_mfma_f32_16x16x32_bf16 v[30:33], v[140:143], v[208:211], v[30:33]
	v_mfma_f32_16x16x32_bf16 v[26:29], v[148:151], v[208:211], v[26:29]
	v_mfma_f32_16x16x32_bf16 v[14:17], v[140:143], v[234:237], v[14:17]
	v_mfma_f32_16x16x32_bf16 v[10:13], v[148:151], v[234:237], v[10:13]
	s_setprio 0
	s_setprio 1
	v_mfma_f32_16x16x32_bf16 v[54:57], v[152:155], v[168:171], v[54:57]
	v_mfma_f32_16x16x32_bf16 v[50:53], v[160:163], v[168:171], v[50:53]
	v_mfma_f32_16x16x32_bf16 v[38:41], v[152:155], v[196:199], v[38:41]
	v_mfma_f32_16x16x32_bf16 v[34:37], v[160:163], v[196:199], v[34:37]
	v_mfma_f32_16x16x32_bf16 v[22:25], v[152:155], v[204:207], v[22:25]
	v_mfma_f32_16x16x32_bf16 v[18:21], v[160:163], v[204:207], v[18:21]
	v_mfma_f32_16x16x32_bf16 v[6:9], v[152:155], v[212:215], v[6:9]
	v_mfma_f32_16x16x32_bf16 v[2:5], v[160:163], v[212:215], v[2:5]
	v_mfma_f32_16x16x32_bf16 v[54:57], v[156:159], v[172:175], v[54:57]
	v_mfma_f32_16x16x32_bf16 v[50:53], v[164:167], v[172:175], v[50:53]
	v_mfma_f32_16x16x32_bf16 v[38:41], v[156:159], v[200:203], v[38:41]
	v_mfma_f32_16x16x32_bf16 v[34:37], v[164:167], v[200:203], v[34:37]
	v_mfma_f32_16x16x32_bf16 v[22:25], v[156:159], v[208:211], v[22:25]
	v_mfma_f32_16x16x32_bf16 v[18:21], v[164:167], v[208:211], v[18:21]
	v_mfma_f32_16x16x32_bf16 v[6:9], v[156:159], v[234:237], v[6:9]
	v_mfma_f32_16x16x32_bf16 v[2:5], v[164:167], v[234:237], v[2:5]
	s_setprio 0
	s_barrier
	s_add_i32 s78, s78, 2
	s_add_u32 s76, s76, 0x100
	s_addc_u32 s77, s77, 0
	s_cmp_gt_u32 s78, 29
	s_mov_b64 s[20:21], s[22:23]

;     __device__ bool next(int i, Unit& u) const { if (!so.next(i >> 1, u)) return false; u.kind = i & 1; return true; }
; #define PG8_STAGE(bufoff, gbase, voff) do { _Pragma("unroll") for (int _i = 0; _i < 2; ++_i) \
;         __builtin_amdgcn_global_load_lds((const unsigned*)((const char*)(gbase) + (voff)[_i]), (LAS unsigned*)(lds + (bufoff) + ldsw + _i * 8192), 16, 0, 0); } while (0)
; #define PG8_LDA(dst, b, h) do { _Pragma("unroll") for (int m = 0; m < 4; ++m) _Pragma("unroll") for (int k = 0; k < 2; ++k) dst[m][k] = *(const LAS bf16x8*)(lds + PG8_SA(b, h) + aoff + m * 2048 + k * 1024); } while (0)
; #define PG8_LDB(dst, b, h) do { _Pragma("unroll") for (int n = 0; n < 2; ++n) _Pragma("unroll") for (int k = 0; k < 2; ++k) dst[n][k] = *(const LAS bf16x8*)(lds + PG8_SB(b, h) + boff + n * 2048 + k * 1024); } while (0)
; #define PG8_WAIT_V(n) asm volatile("s_waitcnt vmcnt(" #n ")" ::: "memory")
; #define PG8_WAIT_L(n) asm volatile("s_waitcnt lgkmcnt(" #n ")" ::: "memory")
; #define PG8_BAR __builtin_amdgcn_s_barrier()
; template <class Epi, class Sched, bool ALIGN_EPI = true, bool SP2 = true>
; __device__ __forceinline__ void gemm_phase(LAS unsigned char* lds, const Gemm g, const Sched& S, const Epi& E) {
;     ...
;         const bool has_next = S.next(ui + 1, nxt);
;         const char* nA = has_next ? (const char*)(nxt.kind ? g.A1 : g.A0) + (size_t)nxt.pm * tstep : cA; const char* nB = has_next ? (const char*)(nxt.kind ? g.B1 : g.B0) + (size_t)nxt.pn * tstep : cB;
;         for (int t = 0; t < nt; t += 2) {
;             const bool last = (t == nt - 2);
;             const char* a1 = cA + (size_t)(t + 1) * kstep;
;             const char* a2 = last ? nA : cA + (size_t)(t + 2) * kstep; const char* b2 = last ? nB : cB + (size_t)(t + 2) * kstep;
;             const char* a3 = a2 + kstep; const char* b3 = b2 + kstep;
;             if constexpr (SP2) {
;             PG8_LDB(B0, 0, 0); PG8_LDB(B1, 0, 1); PG8_SCHED; PG8_LDA(At, 0, 0); PG8_STAGE(PG8_SA(1, 1), a1 + hstep, voffA);
;             PG8_WAIT_V(8); PG8_WAIT_L(0); PG8_BAR; PG8_MMA(0, 0, At, B0); PG8_MMA(0, 1, At, B1); PG8_BAR; PG8_SCHED;
;             PG8_LDA(At, 0, 1); PG8_STAGE(PG8_SB(0, 0), b2, voffB); PG8_STAGE(PG8_SB(0, 1), b2 + hstep, voffB); PG8_STAGE(PG8_SA(0, 0), a2, voffA);
;             PG8_WAIT_V(8); PG8_WAIT_L(0); PG8_BAR; PG8_MMA(1, 0, At, B0); PG8_MMA(1, 1, At, B1); PG8_BAR; PG8_SCHED;
.LBB0_870:
	s_ashr_i32 s17, s16, 31
	s_lshl_b64 s[18:19], s[16:17], 20
	s_add_u32 s18, s88, s18
	s_addc_u32 s19, s89, s19
	s_and_b64 s[20:21], s[8:9], exec
	s_cselect_b32 s17, s19, s5
	s_cselect_b32 s70, s18, s4
	s_ashr_i32 s15, s14, 31
	s_lshl_b64 s[20:21], s[14:15], 20
	s_add_u32 s20, s24, s20
	s_addc_u32 s21, s25, s21
	s_and_b64 s[22:23], s[8:9], exec
	s_cselect_b32 s15, s21, s7
	s_cselect_b32 s71, s20, s6
	s_add_u32 s4, s4, 0x80080
	s_addc_u32 s5, s5, 0
	s_add_u32 s72, s6, 0x100
	s_addc_u32 s73, s7, 0
	s_mov_b32 s74, -2
	s_add_u32 s6, s4, 0xfff80080
	s_addc_u32 s7, s5, -1
	s_add_i32 s58, 0, 0x10000
	s_cmp_eq_u32 s74, 28
	s_cselect_b32 s23, s17, s7
	s_cselect_b32 s22, s70, s6
	v_add_u32_e32 v148, s58, v153
	s_cselect_b32 s7, s15, s73
	s_cselect_b32 s6, s71, s72
	s_add_i32 s75, 0, 0x14000
	ds_read_b128 v[140:143], v148
	ds_read_b128 v[144:147], v148 offset:1024
	ds_read_b128 v[160:163], v148 offset:2048
	ds_read_b128 v[164:167], v148 offset:3072
	v_add_u32_e32 v148, s75, v153
	ds_read_b128 v[168:171], v148
	ds_read_b128 v[172:175], v148 offset:1024
	ds_read_b128 v[176:179], v148 offset:2048
	ds_read_b128 v[194:197], v148 offset:3072
	v_lshl_add_u64 v[148:149], s[4:5], 0, v[136:137]
	s_add_i32 m0, s27, 0xc000
	ds_read_b128 v[198:201], v159
	ds_read_b128 v[202:205], v159 offset:1024
	ds_read_b128 v[206:209], v159 offset:2048
	ds_read_b128 v[210:213], v159 offset:3072
	ds_read_b128 v[234:237], v159 offset:4096
	ds_read_b128 v[238:241], v159 offset:5120
	ds_read_b128 v[242:245], v159 offset:6144
	ds_read_b128 v[246:249], v159 offset:7168
	global_load_lds_dwordx4 v[148:149], off
	v_lshl_add_u64 v[148:149], s[4:5], 0, v[138:139]
	s_add_i32 m0, s27, 0xe000
	s_nop 0
	global_load_lds_dwordx4 v[148:149], off
	s_waitcnt vmcnt(8)
	s_waitcnt lgkmcnt(0)
	s_barrier
	s_setprio 1
	s_waitcnt lgkmcnt(0)
	v_mfma_f32_16x16x32_bf16 v[126:129], v[140:143], v[198:201], 0
	v_mfma_f32_16x16x32_bf16 v[118:121], v[160:163], v[198:201], 0
	v_mfma_f32_16x16x32_bf16 v[110:113], v[140:143], v[206:209], 0
	v_mfma_f32_16x16x32_bf16 v[102:105], v[160:163], v[206:209], 0
	v_mfma_f32_16x16x32_bf16 v[94:97], v[140:143], v[234:237], 0
	v_mfma_f32_16x16x32_bf16 v[86:89], v[160:163], v[234:237], 0
	v_mfma_f32_16x16x32_bf16 v[78:81], v[140:143], v[242:245], 0
	v_mfma_f32_16x16x32_bf16 v[70:73], v[160:163], v[242:245], 0
	v_mfma_f32_16x16x32_bf16 v[126:129], v[144:147], v[202:205], v[126:129]
	v_mfma_f32_16x16x32_bf16 v[118:121], v[164:167], v[202:205], v[118:121]
	v_mfma_f32_16x16x32_bf16 v[110:113], v[144:147], v[210:213], v[110:113]
	v_mfma_f32_16x16x32_bf16 v[102:105], v[164:167], v[210:213], v[102:105]
	v_mfma_f32_16x16x32_bf16 v[94:97], v[144:147], v[238:241], v[94:97]
	v_mfma_f32_16x16x32_bf16 v[86:89], v[164:167], v[238:241], v[86:89]
	v_mfma_f32_16x16x32_bf16 v[78:81], v[144:147], v[246:249], v[78:81]
	v_mfma_f32_16x16x32_bf16 v[70:73], v[164:167], v[246:249], v[70:73]
	s_setprio 0
	s_setprio 1
	v_mfma_f32_16x16x32_bf16 v[122:125], v[168:171], v[198:201], 0
	v_mfma_f32_16x16x32_bf16 v[114:117], v[176:179], v[198:201], 0
	v_mfma_f32_16x16x32_bf16 v[106:109], v[168:171], v[206:209], 0
	v_mfma_f32_16x16x32_bf16 v[98:101], v[176:179], v[206:209], 0
	v_mfma_f32_16x16x32_bf16 v[90:93], v[168:171], v[234:237], 0
	v_mfma_f32_16x16x32_bf16 v[82:85], v[176:179], v[234:237], 0
	v_mfma_f32_16x16x32_bf16 v[74:77], v[168:171], v[242:245], 0
	v_mfma_f32_16x16x32_bf16 v[66:69], v[176:179], v[242:245], 0
	v_mfma_f32_16x16x32_bf16 v[122:125], v[172:175], v[202:205], v[122:125]
	v_mfma_f32_16x16x32_bf16 v[114:117], v[194:197], v[202:205], v[114:117]
	v_mfma_f32_16x16x32_bf16 v[106:109], v[172:175], v[210:213], v[106:109]
	v_mfma_f32_16x16x32_bf16 v[98:101], v[194:197], v[210:213], v[98:101]
	v_mfma_f32_16x16x32_bf16 v[90:93], v[172:175], v[238:241], v[90:93]
	v_mfma_f32_16x16x32_bf16 v[82:85], v[194:197], v[238:241], v[82:85]
	v_mfma_f32_16x16x32_bf16 v[74:77], v[172:175], v[246:249], v[74:77]
	v_mfma_f32_16x16x32_bf16 v[66:69], v[194:197], v[246:249], v[66:69]
	s_setprio 0
	s_barrier
	s_add_i32 s58, s58, s26
	v_lshl_add_u64 v[148:149], s[6:7], 0, v[0:1]
	s_mov_b32 m0, s58
	ds_read_b128 v[198:201], v159 offset:16384
	ds_read_b128 v[202:205], v159 offset:17408
	ds_read_b128 v[206:209], v159 offset:18432
	ds_read_b128 v[210:213], v159 offset:19456
	ds_read_b128 v[234:237], v159 offset:20480
	ds_read_b128 v[238:241], v159 offset:21504
	ds_read_b128 v[242:245], v159 offset:22528
	ds_read_b128 v[246:249], v159 offset:23552
	global_load_lds_dwordx4 v[148:149], off
	s_add_i32 m0, s58, 0x2000
	s_add_u32 s58, s6, 0x80000
	v_lshl_add_u64 v[156:157], s[6:7], 0, v[130:131]
	s_addc_u32 s59, s7, 0
	s_add_i32 s75, s75, s26
	global_load_lds_dwordx4 v[156:157], off
	v_lshl_add_u64 v[214:215], s[58:59], 0, v[0:1]
	s_mov_b32 m0, s75
	v_lshl_add_u64 v[224:225], s[22:23], 0, v[132:133]
	global_load_lds_dwordx4 v[214:215], off
	v_lshl_add_u64 v[214:215], s[58:59], 0, v[130:131]
	s_add_i32 m0, s75, 0x2000
	s_nop 0
	global_load_lds_dwordx4 v[214:215], off
	v_lshl_add_u64 v[214:215], s[22:23], 0, v[134:135]
	s_mov_b32 m0, s27
	s_nop 0
	global_load_lds_dwordx4 v[214:215], off
	s_mov_b32 m0, s28
	s_nop 0
	global_load_lds_dwordx4 v[224:225], off
	s_waitcnt vmcnt(8)
	s_waitcnt lgkmcnt(0)
	s_barrier
; #define PG8_STAGE(bufoff, gbase, voff) do { _Pragma("unroll") for (int _i = 0; _i < 2; ++_i) \
;         __builtin_amdgcn_global_load_lds((const unsigned*)((const char*)(gbase) + (voff)[_i]), (LAS unsigned*)(lds + (bufoff) + ldsw + _i * 8192), 16, 0, 0); } while (0)
; #define PG8_LDA(dst, b, h) do { _Pragma("unroll") for (int m = 0; m < 4; ++m) _Pragma("unroll") for (int k = 0; k < 2; ++k) dst[m][k] = *(const LAS bf16x8*)(lds + PG8_SA(b, h) + aoff + m * 2048 + k * 1024); } while (0)
; #define PG8_LDB(dst, b, h) do { _Pragma("unroll") for (int n = 0; n < 2; ++n) _Pragma("unroll") for (int k = 0; k < 2; ++k) dst[n][k] = *(const LAS bf16x8*)(lds + PG8_SB(b, h) + boff + n * 2048 + k * 1024); } while (0)
; #define PG8_MMA(ai, bj, At, Bt) do { __builtin_amdgcn_s_setprio(1); _Pragma("unroll") for (int m = 0; m < 4; ++m) _Pragma("unroll") for (int n = 0; n < 2; ++n) _Pragma("unroll") for (int k = 0; k < 2; ++k) \
;         acc[ai][bj][m][n] = __builtin_amdgcn_mfma_f32_16x16x32_bf16(Bt[n][k], At[m][k], acc[ai][bj][m][n], 0, 0, 0); __builtin_amdgcn_s_setprio(0); } while (0)
; #define PG8_WAIT_V(n) asm volatile("s_waitcnt vmcnt(" #n ")" ::: "memory")
; #define PG8_WAIT_L(n) asm volatile("s_waitcnt lgkmcnt(" #n ")" ::: "memory")
; #define PG8_BAR __builtin_amdgcn_s_barrier()
; #define PG8_SCHED __builtin_amdgcn_sched_barrier(0)
; template <class Epi, class Sched, bool ALIGN_EPI = true, bool SP2 = true>
; __device__ __forceinline__ void gemm_phase(LAS unsigned char* lds, const Gemm g, const Sched& S, const Epi& E) {
;     ...
;             PG8_WAIT_V(8); PG8_WAIT_L(0); PG8_BAR; PG8_MMA(1, 0, At, B0); PG8_MMA(1, 1, At, B1); PG8_BAR; PG8_SCHED;
;             PG8_LDB(B0, 1, 0); PG8_LDB(B1, 1, 1); PG8_SCHED; PG8_LDA(At, 1, 0); PG8_STAGE(PG8_SA(0, 1), a2 + hstep, voffA);
;             PG8_WAIT_V(8); PG8_WAIT_L(0); PG8_BAR; PG8_MMA(0, 0, At, B0); PG8_MMA(0, 1, At, B1); PG8_BAR; PG8_SCHED;
;             PG8_LDA(At, 1, 1); PG8_STAGE(PG8_SB(1, 0), b3, voffB); PG8_STAGE(PG8_SB(1, 1), b3 + hstep, voffB); PG8_STAGE(PG8_SA(1, 0), a3, voffA);
;             PG8_WAIT_V(8); PG8_WAIT_L(0); PG8_BAR; PG8_MMA(1, 0, At, B0); PG8_MMA(1, 1, At, B1); PG8_BAR; PG8_SCHED;
	s_setprio 1
	s_waitcnt lgkmcnt(0)
	v_mfma_f32_16x16x32_bf16 v[62:65], v[140:143], v[198:201], 0
	v_mfma_f32_16x16x32_bf16 v[54:57], v[160:163], v[198:201], 0
	v_mfma_f32_16x16x32_bf16 v[46:49], v[140:143], v[206:209], 0
	v_mfma_f32_16x16x32_bf16 v[38:41], v[160:163], v[206:209], 0
	v_mfma_f32_16x16x32_bf16 v[30:33], v[140:143], v[234:237], 0
	v_mfma_f32_16x16x32_bf16 v[22:25], v[160:163], v[234:237], 0
	v_mfma_f32_16x16x32_bf16 v[14:17], v[140:143], v[242:245], 0
	v_mfma_f32_16x16x32_bf16 v[6:9], v[160:163], v[242:245], 0
	v_mfma_f32_16x16x32_bf16 v[62:65], v[144:147], v[202:205], v[62:65]
	v_mfma_f32_16x16x32_bf16 v[54:57], v[164:167], v[202:205], v[54:57]
	v_mfma_f32_16x16x32_bf16 v[46:49], v[144:147], v[210:213], v[46:49]
	v_mfma_f32_16x16x32_bf16 v[38:41], v[164:167], v[210:213], v[38:41]
	v_mfma_f32_16x16x32_bf16 v[30:33], v[144:147], v[238:241], v[30:33]
	v_mfma_f32_16x16x32_bf16 v[22:25], v[164:167], v[238:241], v[22:25]
	v_mfma_f32_16x16x32_bf16 v[14:17], v[144:147], v[246:249], v[14:17]
	v_mfma_f32_16x16x32_bf16 v[6:9], v[164:167], v[246:249], v[6:9]
	s_setprio 0
	s_setprio 1
	v_mfma_f32_16x16x32_bf16 v[58:61], v[168:171], v[198:201], 0
	v_mfma_f32_16x16x32_bf16 v[50:53], v[176:179], v[198:201], 0
	v_mfma_f32_16x16x32_bf16 v[42:45], v[168:171], v[206:209], 0
	v_mfma_f32_16x16x32_bf16 v[34:37], v[176:179], v[206:209], 0
	v_mfma_f32_16x16x32_bf16 v[26:29], v[168:171], v[234:237], 0
	v_mfma_f32_16x16x32_bf16 v[18:21], v[176:179], v[234:237], 0
	v_mfma_f32_16x16x32_bf16 v[10:13], v[168:171], v[242:245], 0
	v_mfma_f32_16x16x32_bf16 v[2:5], v[176:179], v[242:245], 0
	v_mfma_f32_16x16x32_bf16 v[58:61], v[172:175], v[202:205], v[58:61]
	v_mfma_f32_16x16x32_bf16 v[50:53], v[194:197], v[202:205], v[50:53]
	v_mfma_f32_16x16x32_bf16 v[42:45], v[172:175], v[210:213], v[42:45]
	v_mfma_f32_16x16x32_bf16 v[34:37], v[194:197], v[210:213], v[34:37]
	v_mfma_f32_16x16x32_bf16 v[26:29], v[172:175], v[238:241], v[26:29]
	v_mfma_f32_16x16x32_bf16 v[18:21], v[194:197], v[238:241], v[18:21]
	v_mfma_f32_16x16x32_bf16 v[10:13], v[172:175], v[246:249], v[10:13]
	v_mfma_f32_16x16x32_bf16 v[2:5], v[194:197], v[246:249], v[2:5]
	s_setprio 0
	s_barrier
	s_add_i32 s58, 0, 0x18000
	v_add_u32_e32 v150, s58, v153
	s_add_i32 s59, 0, 0x1c000
	ds_read_b128 v[140:143], v150
	ds_read_b128 v[144:147], v150 offset:1024
	ds_read_b128 v[160:163], v150 offset:2048
	ds_read_b128 v[164:167], v150 offset:3072
	v_add_u32_e32 v150, s59, v153
	ds_read_b128 v[168:171], v150
	ds_read_b128 v[172:175], v150 offset:1024
	ds_read_b128 v[176:179], v150 offset:2048
	ds_read_b128 v[194:197], v150 offset:3072
	s_add_u32 s22, s22, 0x80000
	s_addc_u32 s23, s23, 0
	s_mov_b32 m0, s29
	v_lshl_add_u64 v[250:251], s[22:23], 0, v[134:135]
	ds_read_b128 v[198:201], v159 offset:32768
	ds_read_b128 v[202:205], v159 offset:33792
	ds_read_b128 v[206:209], v159 offset:34816
	ds_read_b128 v[210:213], v159 offset:35840
	ds_read_b128 v[234:237], v159 offset:36864
	ds_read_b128 v[238:241], v159 offset:37888
	ds_read_b128 v[242:245], v159 offset:38912
	ds_read_b128 v[246:249], v159 offset:39936
	global_load_lds_dwordx4 v[250:251], off
	v_lshl_add_u64 v[250:251], s[22:23], 0, v[132:133]
	s_mov_b32 m0, s30
	s_nop 0
	global_load_lds_dwordx4 v[250:251], off
	s_waitcnt vmcnt(8)
	s_waitcnt lgkmcnt(0)
	s_barrier
	s_setprio 1
	s_waitcnt lgkmcnt(0)
	v_mfma_f32_16x16x32_bf16 v[126:129], v[140:143], v[198:201], v[126:129]
	v_mfma_f32_16x16x32_bf16 v[118:121], v[160:163], v[198:201], v[118:121]
	v_mfma_f32_16x16x32_bf16 v[110:113], v[140:143], v[206:209], v[110:113]
	v_mfma_f32_16x16x32_bf16 v[102:105], v[160:163], v[206:209], v[102:105]
	v_mfma_f32_16x16x32_bf16 v[94:97], v[140:143], v[234:237], v[94:97]
	v_mfma_f32_16x16x32_bf16 v[86:89], v[160:163], v[234:237], v[86:89]
	v_mfma_f32_16x16x32_bf16 v[78:81], v[140:143], v[242:245], v[78:81]
	v_mfma_f32_16x16x32_bf16 v[70:73], v[160:163], v[242:245], v[70:73]
	v_mfma_f32_16x16x32_bf16 v[126:129], v[144:147], v[202:205], v[126:129]
	v_mfma_f32_16x16x32_bf16 v[118:121], v[164:167], v[202:205], v[118:121]
	v_mfma_f32_16x16x32_bf16 v[110:113], v[144:147], v[210:213], v[110:113]
	v_mfma_f32_16x16x32_bf16 v[102:105], v[164:167], v[210:213], v[102:105]
	v_mfma_f32_16x16x32_bf16 v[94:97], v[144:147], v[238:241], v[94:97]
	v_mfma_f32_16x16x32_bf16 v[86:89], v[164:167], v[238:241], v[86:89]
	v_mfma_f32_16x16x32_bf16 v[78:81], v[144:147], v[246:249], v[78:81]
	v_mfma_f32_16x16x32_bf16 v[70:73], v[164:167], v[246:249], v[70:73]
	s_setprio 0
	s_setprio 1
	v_mfma_f32_16x16x32_bf16 v[122:125], v[168:171], v[198:201], v[122:125]
	v_mfma_f32_16x16x32_bf16 v[114:117], v[176:179], v[198:201], v[114:117]
	v_mfma_f32_16x16x32_bf16 v[106:109], v[168:171], v[206:209], v[106:109]
	v_mfma_f32_16x16x32_bf16 v[98:101], v[176:179], v[206:209], v[98:101]
	v_mfma_f32_16x16x32_bf16 v[90:93], v[168:171], v[234:237], v[90:93]
	v_mfma_f32_16x16x32_bf16 v[82:85], v[176:179], v[234:237], v[82:85]
	v_mfma_f32_16x16x32_bf16 v[74:77], v[168:171], v[242:245], v[74:77]
	v_mfma_f32_16x16x32_bf16 v[66:69], v[176:179], v[242:245], v[66:69]
	v_mfma_f32_16x16x32_bf16 v[122:125], v[172:175], v[202:205], v[122:125]
	v_mfma_f32_16x16x32_bf16 v[114:117], v[194:197], v[202:205], v[114:117]
	v_mfma_f32_16x16x32_bf16 v[106:109], v[172:175], v[210:213], v[106:109]
	v_mfma_f32_16x16x32_bf16 v[98:101], v[194:197], v[210:213], v[98:101]
	v_mfma_f32_16x16x32_bf16 v[90:93], v[172:175], v[238:241], v[90:93]
	v_mfma_f32_16x16x32_bf16 v[82:85], v[194:197], v[238:241], v[82:85]
	v_mfma_f32_16x16x32_bf16 v[74:77], v[172:175], v[246:249], v[74:77]
	v_mfma_f32_16x16x32_bf16 v[66:69], v[194:197], v[246:249], v[66:69]
	s_setprio 0
	s_barrier
; #define PG8_STAGE(bufoff, gbase, voff) do { _Pragma("unroll") for (int _i = 0; _i < 2; ++_i) \
;         __builtin_amdgcn_global_load_lds((const unsigned*)((const char*)(gbase) + (voff)[_i]), (LAS unsigned*)(lds + (bufoff) + ldsw + _i * 8192), 16, 0, 0); } while (0)
; #define PG8_LDA(dst, b, h) do { _Pragma("unroll") for (int m = 0; m < 4; ++m) _Pragma("unroll") for (int k = 0; k < 2; ++k) dst[m][k] = *(const LAS bf16x8*)(lds + PG8_SA(b, h) + aoff + m * 2048 + k * 1024); } while (0)
; #define PG8_MMA(ai, bj, At, Bt) do { __builtin_amdgcn_s_setprio(1); _Pragma("unroll") for (int m = 0; m < 4; ++m) _Pragma("unroll") for (int n = 0; n < 2; ++n) _Pragma("unroll") for (int k = 0; k < 2; ++k) \
;         acc[ai][bj][m][n] = __builtin_amdgcn_mfma_f32_16x16x32_bf16(Bt[n][k], At[m][k], acc[ai][bj][m][n], 0, 0, 0); __builtin_amdgcn_s_setprio(0); } while (0)
; #define PG8_WAIT_V(n) asm volatile("s_waitcnt vmcnt(" #n ")" ::: "memory")
; #define PG8_WAIT_L(n) asm volatile("s_waitcnt lgkmcnt(" #n ")" ::: "memory")
; #define PG8_BAR __builtin_amdgcn_s_barrier()
; #define PG8_SCHED __builtin_amdgcn_sched_barrier(0)
; template <class Epi, class Sched, bool ALIGN_EPI = true, bool SP2 = true>
; __device__ __forceinline__ void gemm_phase(LAS unsigned char* lds, const Gemm g, const Sched& S, const Epi& E) {
;     ...
;             PG8_LDA(At, 1, 1); PG8_STAGE(PG8_SB(1, 0), b3, voffB); PG8_STAGE(PG8_SB(1, 1), b3 + hstep, voffB); PG8_STAGE(PG8_SA(1, 0), a3, voffA);
;             PG8_WAIT_V(8); PG8_WAIT_L(0); PG8_BAR; PG8_MMA(1, 0, At, B0); PG8_MMA(1, 1, At, B1); PG8_BAR; PG8_SCHED;
	s_add_i32 s22, s58, s26
	v_lshl_add_u64 v[148:149], v[148:149], 0, s[92:93]
	s_mov_b32 m0, s22
	ds_read_b128 v[198:201], v159 offset:49152
	ds_read_b128 v[202:205], v159 offset:50176
	ds_read_b128 v[206:209], v159 offset:51200
	ds_read_b128 v[210:213], v159 offset:52224
	ds_read_b128 v[234:237], v159 offset:53248
	ds_read_b128 v[238:241], v159 offset:54272
	ds_read_b128 v[242:245], v159 offset:55296
	ds_read_b128 v[246:249], v159 offset:56320
	global_load_lds_dwordx4 v[148:149], off
	s_add_i32 m0, s22, 0x2000
	s_add_u32 s6, s6, 0x80080
	v_lshl_add_u64 v[148:149], v[156:157], 0, s[92:93]
	s_addc_u32 s7, s7, 0
	s_add_i32 s22, s59, s26
	global_load_lds_dwordx4 v[148:149], off
	v_lshl_add_u64 v[148:149], s[6:7], 0, v[0:1]
	s_mov_b32 m0, s22
	s_nop 0
	global_load_lds_dwordx4 v[148:149], off
	v_lshl_add_u64 v[148:149], s[6:7], 0, v[130:131]
	s_add_i32 m0, s22, 0x2000
	s_nop 0
	global_load_lds_dwordx4 v[148:149], off
	v_lshl_add_u64 v[148:149], v[214:215], 0, s[92:93]
	s_mov_b32 m0, s31
	s_nop 0
	global_load_lds_dwordx4 v[148:149], off
	v_lshl_add_u64 v[148:149], v[224:225], 0, s[92:93]
	s_mov_b32 m0, s34
	s_nop 0
	global_load_lds_dwordx4 v[148:149], off
	s_waitcnt vmcnt(8)
	s_waitcnt lgkmcnt(0)
	s_barrier
	s_setprio 1
	s_waitcnt lgkmcnt(0)
	v_mfma_f32_16x16x32_bf16 v[62:65], v[140:143], v[198:201], v[62:65]
	v_mfma_f32_16x16x32_bf16 v[54:57], v[160:163], v[198:201], v[54:57]
	v_mfma_f32_16x16x32_bf16 v[46:49], v[140:143], v[206:209], v[46:49]
	v_mfma_f32_16x16x32_bf16 v[38:41], v[160:163], v[206:209], v[38:41]
	v_mfma_f32_16x16x32_bf16 v[30:33], v[140:143], v[234:237], v[30:33]
	v_mfma_f32_16x16x32_bf16 v[22:25], v[160:163], v[234:237], v[22:25]
	v_mfma_f32_16x16x32_bf16 v[14:17], v[140:143], v[242:245], v[14:17]
	v_mfma_f32_16x16x32_bf16 v[6:9], v[160:163], v[242:245], v[6:9]
	v_mfma_f32_16x16x32_bf16 v[62:65], v[144:147], v[202:205], v[62:65]
	v_mfma_f32_16x16x32_bf16 v[54:57], v[164:167], v[202:205], v[54:57]
	v_mfma_f32_16x16x32_bf16 v[46:49], v[144:147], v[210:213], v[46:49]
	v_mfma_f32_16x16x32_bf16 v[38:41], v[164:167], v[210:213], v[38:41]
	v_mfma_f32_16x16x32_bf16 v[30:33], v[144:147], v[238:241], v[30:33]
	v_mfma_f32_16x16x32_bf16 v[22:25], v[164:167], v[238:241], v[22:25]
	v_mfma_f32_16x16x32_bf16 v[14:17], v[144:147], v[246:249], v[14:17]
	v_mfma_f32_16x16x32_bf16 v[6:9], v[164:167], v[246:249], v[6:9]
	s_setprio 0
	s_setprio 1
	v_mfma_f32_16x16x32_bf16 v[58:61], v[168:171], v[198:201], v[58:61]
	v_mfma_f32_16x16x32_bf16 v[50:53], v[176:179], v[198:201], v[50:53]
	v_mfma_f32_16x16x32_bf16 v[42:45], v[168:171], v[206:209], v[42:45]
	v_mfma_f32_16x16x32_bf16 v[34:37], v[176:179], v[206:209], v[34:37]
	v_mfma_f32_16x16x32_bf16 v[26:29], v[168:171], v[234:237], v[26:29]
	v_mfma_f32_16x16x32_bf16 v[18:21], v[176:179], v[234:237], v[18:21]
	v_mfma_f32_16x16x32_bf16 v[10:13], v[168:171], v[242:245], v[10:13]
	v_mfma_f32_16x16x32_bf16 v[2:5], v[176:179], v[242:245], v[2:5]
	v_mfma_f32_16x16x32_bf16 v[58:61], v[172:175], v[202:205], v[58:61]
	v_mfma_f32_16x16x32_bf16 v[50:53], v[194:197], v[202:205], v[50:53]
	v_mfma_f32_16x16x32_bf16 v[42:45], v[172:175], v[210:213], v[42:45]
	v_mfma_f32_16x16x32_bf16 v[34:37], v[194:197], v[210:213], v[34:37]
	v_mfma_f32_16x16x32_bf16 v[26:29], v[172:175], v[238:241], v[26:29]
	v_mfma_f32_16x16x32_bf16 v[18:21], v[194:197], v[238:241], v[18:21]
	v_mfma_f32_16x16x32_bf16 v[10:13], v[172:175], v[246:249], v[10:13]
	v_mfma_f32_16x16x32_bf16 v[2:5], v[194:197], v[246:249], v[2:5]
	s_setprio 0
	s_barrier
	s_add_i32 s74, s74, 2
	s_add_u32 s4, s4, 0x100
	s_addc_u32 s5, s5, 0
	s_add_u32 s72, s72, 0x100
	s_addc_u32 s73, s73, 0
	s_cmp_gt_u32 s74, 29

;     __device__ bool next(int i, Unit& u) const { if (!so.next(i >> 1, u)) return false; u.kind = i & 1; return true; }
; #define PG8_STAGE(bufoff, gbase, voff) do { _Pragma("unroll") for (int _i = 0; _i < 2; ++_i) \
;         __builtin_amdgcn_global_load_lds((const unsigned*)((const char*)(gbase) + (voff)[_i]), (LAS unsigned*)(lds + (bufoff) + ldsw + _i * 8192), 16, 0, 0); } while (0)
; #define PG8_LDA(dst, b, h) do { _Pragma("unroll") for (int m = 0; m < 4; ++m) _Pragma("unroll") for (int k = 0; k < 2; ++k) dst[m][k] = *(const LAS bf16x8*)(lds + PG8_SA(b, h) + aoff + m * 2048 + k * 1024); } while (0)
; #define PG8_LDB(dst, b, h) do { _Pragma("unroll") for (int n = 0; n < 2; ++n) _Pragma("unroll") for (int k = 0; k < 2; ++k) dst[n][k] = *(const LAS bf16x8*)(lds + PG8_SB(b, h) + boff + n * 2048 + k * 1024); } while (0)
; #define PG8_WAIT_V(n) asm volatile("s_waitcnt vmcnt(" #n ")" ::: "memory")
; #define PG8_WAIT_L(n) asm volatile("s_waitcnt lgkmcnt(" #n ")" ::: "memory")
; #define PG8_BAR __builtin_amdgcn_s_barrier()
; template <class Epi, class Sched, bool ALIGN_EPI = true, bool SP2 = true>
; __device__ __forceinline__ void gemm_phase(LAS unsigned char* lds, const Gemm g, const Sched& S, const Epi& E) {
;     ...
;         const bool has_next = S.next(ui + 1, nxt);
;         const char* nA = has_next ? (const char*)(nxt.kind ? g.A1 : g.A0) + (size_t)nxt.pm * tstep : cA; const char* nB = has_next ? (const char*)(nxt.kind ? g.B1 : g.B0) + (size_t)nxt.pn * tstep : cB;
;         for (int t = 0; t < nt; t += 2) {
;             const bool last = (t == nt - 2);
;             const char* a1 = cA + (size_t)(t + 1) * kstep;
;             const char* a2 = last ? nA : cA + (size_t)(t + 2) * kstep; const char* b2 = last ? nB : cB + (size_t)(t + 2) * kstep;
;             const char* a3 = a2 + kstep; const char* b3 = b2 + kstep;
;             if constexpr (SP2) {
;             PG8_LDB(B0, 0, 0); PG8_LDB(B1, 0, 1); PG8_SCHED; PG8_LDA(At, 0, 0); PG8_STAGE(PG8_SA(1, 1), a1 + hstep, voffA);
;             PG8_WAIT_V(8); PG8_WAIT_L(0); PG8_BAR; PG8_MMA(0, 0, At, B0); PG8_MMA(0, 1, At, B1); PG8_BAR; PG8_SCHED;
;             PG8_LDA(At, 0, 1); PG8_STAGE(PG8_SB(0, 0), b2, voffB); PG8_STAGE(PG8_SB(0, 1), b2 + hstep, voffB); PG8_STAGE(PG8_SA(0, 0), a2, voffA);
;             PG8_WAIT_V(8); PG8_WAIT_L(0); PG8_BAR; PG8_MMA(1, 0, At, B0); PG8_MMA(1, 1, At, B1); PG8_BAR; PG8_SCHED;
.LBB0_990:
	s_add_u32 s72, s18, 0x100
	s_addc_u32 s73, s19, 0
	s_mov_b32 s74, -2
	s_waitcnt lgkmcnt(0)
	s_add_u32 s18, s16, 0x100
	s_addc_u32 s19, s17, 0
	s_add_i32 s58, 0, 0x10000
	s_cmpk_eq_i32 s74, 0x54
	s_cselect_b32 s23, s1, s19
	s_cselect_b32 s22, s0, s18
	s_cselect_b32 s21, s15, s73
	s_cselect_b32 s20, s14, s72
	s_add_i32 s59, 0, 0x14000
	v_add_u32_e32 v148, s58, v179
	v_add_u32_e32 v164, s59, v179
	ds_read_b128 v[136:139], v148
	ds_read_b128 v[140:143], v148 offset:1024
	ds_read_b128 v[144:147], v148 offset:2048
	ds_read_b128 v[148:151], v148 offset:3072
	ds_read_b128 v[152:155], v164
	ds_read_b128 v[156:159], v164 offset:1024
	ds_read_b128 v[160:163], v164 offset:2048
	ds_read_b128 v[164:167], v164 offset:3072
	v_lshl_add_u64 v[176:177], s[16:17], 0, v[132:133]
	s_add_i32 m0, s27, 0xc000
	ds_read_b128 v[168:171], v194
	ds_read_b128 v[172:175], v194 offset:1024
	ds_read_b128 v[196:199], v194 offset:2048
	ds_read_b128 v[200:203], v194 offset:3072
	ds_read_b128 v[204:207], v194 offset:4096
	ds_read_b128 v[208:211], v194 offset:5120
	ds_read_b128 v[212:215], v194 offset:6144
	ds_read_b128 v[234:237], v194 offset:7168
	global_load_lds_dwordx4 v[176:177], off
	v_lshl_add_u64 v[176:177], s[16:17], 0, v[134:135]
	s_add_i32 m0, s27, 0xe000
	s_nop 0
	global_load_lds_dwordx4 v[176:177], off
	s_waitcnt vmcnt(8)
	s_waitcnt lgkmcnt(0)
	s_barrier
	s_setprio 1
	s_waitcnt lgkmcnt(0)
	v_mfma_f32_16x16x32_bf16 v[126:129], v[136:139], v[168:171], 0
	v_mfma_f32_16x16x32_bf16 v[122:125], v[144:147], v[168:171], 0
	v_mfma_f32_16x16x32_bf16 v[110:113], v[136:139], v[196:199], 0
	v_mfma_f32_16x16x32_bf16 v[106:109], v[144:147], v[196:199], 0
	v_mfma_f32_16x16x32_bf16 v[94:97], v[136:139], v[204:207], 0
	v_mfma_f32_16x16x32_bf16 v[90:93], v[144:147], v[204:207], 0
	v_mfma_f32_16x16x32_bf16 v[78:81], v[136:139], v[212:215], 0
	v_mfma_f32_16x16x32_bf16 v[74:77], v[144:147], v[212:215], 0
	v_mfma_f32_16x16x32_bf16 v[126:129], v[140:143], v[172:175], v[126:129]
	v_mfma_f32_16x16x32_bf16 v[122:125], v[148:151], v[172:175], v[122:125]
	v_mfma_f32_16x16x32_bf16 v[110:113], v[140:143], v[200:203], v[110:113]
	v_mfma_f32_16x16x32_bf16 v[106:109], v[148:151], v[200:203], v[106:109]
	v_mfma_f32_16x16x32_bf16 v[94:97], v[140:143], v[208:211], v[94:97]
	v_mfma_f32_16x16x32_bf16 v[90:93], v[148:151], v[208:211], v[90:93]
	v_mfma_f32_16x16x32_bf16 v[78:81], v[140:143], v[234:237], v[78:81]
	v_mfma_f32_16x16x32_bf16 v[74:77], v[148:151], v[234:237], v[74:77]
	s_setprio 0
	s_setprio 1
	v_mfma_f32_16x16x32_bf16 v[118:121], v[152:155], v[168:171], 0
	v_mfma_f32_16x16x32_bf16 v[114:117], v[160:163], v[168:171], 0
	v_mfma_f32_16x16x32_bf16 v[102:105], v[152:155], v[196:199], 0
	v_mfma_f32_16x16x32_bf16 v[98:101], v[160:163], v[196:199], 0
	v_mfma_f32_16x16x32_bf16 v[86:89], v[152:155], v[204:207], 0
	v_mfma_f32_16x16x32_bf16 v[82:85], v[160:163], v[204:207], 0
	v_mfma_f32_16x16x32_bf16 v[70:73], v[152:155], v[212:215], 0
	v_mfma_f32_16x16x32_bf16 v[66:69], v[160:163], v[212:215], 0
	v_mfma_f32_16x16x32_bf16 v[118:121], v[156:159], v[172:175], v[118:121]
	v_mfma_f32_16x16x32_bf16 v[114:117], v[164:167], v[172:175], v[114:117]
	v_mfma_f32_16x16x32_bf16 v[102:105], v[156:159], v[200:203], v[102:105]
	v_mfma_f32_16x16x32_bf16 v[98:101], v[164:167], v[200:203], v[98:101]
	v_mfma_f32_16x16x32_bf16 v[86:89], v[156:159], v[208:211], v[86:89]
	v_mfma_f32_16x16x32_bf16 v[82:85], v[164:167], v[208:211], v[82:85]
	v_mfma_f32_16x16x32_bf16 v[70:73], v[156:159], v[234:237], v[70:73]
	v_mfma_f32_16x16x32_bf16 v[66:69], v[164:167], v[234:237], v[66:69]
	s_setprio 0
	s_barrier
	s_add_i32 s16, s58, s26
	v_lshl_add_u64 v[176:177], s[20:21], 0, v[0:1]
	s_mov_b32 m0, s16
	ds_read_b128 v[168:171], v194 offset:16384
	ds_read_b128 v[172:175], v194 offset:17408
	ds_read_b128 v[196:199], v194 offset:18432
	ds_read_b128 v[200:203], v194 offset:19456
	ds_read_b128 v[204:207], v194 offset:20480
	ds_read_b128 v[208:211], v194 offset:21504
	ds_read_b128 v[212:215], v194 offset:22528
	ds_read_b128 v[234:237], v194 offset:23552
	global_load_lds_dwordx4 v[176:177], off
	s_add_i32 m0, s16, 0x2000
	s_add_u32 s16, s20, 0x160000
	v_lshl_add_u64 v[224:225], s[20:21], 0, v[130:131]
	s_addc_u32 s17, s21, 0
	s_add_i32 s58, s59, s26
	global_load_lds_dwordx4 v[224:225], off
	v_lshl_add_u64 v[238:239], s[16:17], 0, v[0:1]
	s_mov_b32 m0, s58
	v_lshl_add_u64 v[240:241], s[22:23], 0, v[130:131]
	global_load_lds_dwordx4 v[238:239], off
	v_lshl_add_u64 v[238:239], s[16:17], 0, v[130:131]
	s_add_i32 m0, s58, 0x2000
	s_nop 0
	global_load_lds_dwordx4 v[238:239], off
	v_lshl_add_u64 v[238:239], s[22:23], 0, v[0:1]
	s_mov_b32 m0, s27
	s_nop 0
	global_load_lds_dwordx4 v[238:239], off
	s_mov_b32 m0, s28
	s_nop 0
	global_load_lds_dwordx4 v[240:241], off
	s_waitcnt vmcnt(8)
	s_waitcnt lgkmcnt(0)
	s_barrier
; #define PG8_STAGE(bufoff, gbase, voff) do { _Pragma("unroll") for (int _i = 0; _i < 2; ++_i) \
;         __builtin_amdgcn_global_load_lds((const unsigned*)((const char*)(gbase) + (voff)[_i]), (LAS unsigned*)(lds + (bufoff) + ldsw + _i * 8192), 16, 0, 0); } while (0)
; #define PG8_LDA(dst, b, h) do { _Pragma("unroll") for (int m = 0; m < 4; ++m) _Pragma("unroll") for (int k = 0; k < 2; ++k) dst[m][k] = *(const LAS bf16x8*)(lds + PG8_SA(b, h) + aoff + m * 2048 + k * 1024); } while (0)
; #define PG8_LDB(dst, b, h) do { _Pragma("unroll") for (int n = 0; n < 2; ++n) _Pragma("unroll") for (int k = 0; k < 2; ++k) dst[n][k] = *(const LAS bf16x8*)(lds + PG8_SB(b, h) + boff + n * 2048 + k * 1024); } while (0)
; #define PG8_MMA(ai, bj, At, Bt) do { __builtin_amdgcn_s_setprio(1); _Pragma("unroll") for (int m = 0; m < 4; ++m) _Pragma("unroll") for (int n = 0; n < 2; ++n) _Pragma("unroll") for (int k = 0; k < 2; ++k) \
;         acc[ai][bj][m][n] = __builtin_amdgcn_mfma_f32_16x16x32_bf16(Bt[n][k], At[m][k], acc[ai][bj][m][n], 0, 0, 0); __builtin_amdgcn_s_setprio(0); } while (0)
; #define PG8_WAIT_V(n) asm volatile("s_waitcnt vmcnt(" #n ")" ::: "memory")
; #define PG8_WAIT_L(n) asm volatile("s_waitcnt lgkmcnt(" #n ")" ::: "memory")
; #define PG8_BAR __builtin_amdgcn_s_barrier()
; #define PG8_SCHED __builtin_amdgcn_sched_barrier(0)
; template <class Epi, class Sched, bool ALIGN_EPI = true, bool SP2 = true>
; __device__ __forceinline__ void gemm_phase(LAS unsigned char* lds, const Gemm g, const Sched& S, const Epi& E) {
;     ...
;             PG8_WAIT_V(8); PG8_WAIT_L(0); PG8_BAR; PG8_MMA(1, 0, At, B0); PG8_MMA(1, 1, At, B1); PG8_BAR; PG8_SCHED;
;             PG8_LDB(B0, 1, 0); PG8_LDB(B1, 1, 1); PG8_SCHED; PG8_LDA(At, 1, 0); PG8_STAGE(PG8_SA(0, 1), a2 + hstep, voffA);
;             PG8_WAIT_V(8); PG8_WAIT_L(0); PG8_BAR; PG8_MMA(0, 0, At, B0); PG8_MMA(0, 1, At, B1); PG8_BAR; PG8_SCHED;
;             PG8_LDA(At, 1, 1); PG8_STAGE(PG8_SB(1, 0), b3, voffB); PG8_STAGE(PG8_SB(1, 1), b3 + hstep, voffB); PG8_STAGE(PG8_SA(1, 0), a3, voffA);
;             PG8_WAIT_V(8); PG8_WAIT_L(0); PG8_BAR; PG8_MMA(1, 0, At, B0); PG8_MMA(1, 1, At, B1); PG8_BAR; PG8_SCHED;
	s_setprio 1
	s_waitcnt lgkmcnt(0)
	v_mfma_f32_16x16x32_bf16 v[62:65], v[136:139], v[168:171], 0
	v_mfma_f32_16x16x32_bf16 v[58:61], v[144:147], v[168:171], 0
	v_mfma_f32_16x16x32_bf16 v[46:49], v[136:139], v[196:199], 0
	v_mfma_f32_16x16x32_bf16 v[42:45], v[144:147], v[196:199], 0
	v_mfma_f32_16x16x32_bf16 v[30:33], v[136:139], v[204:207], 0
	v_mfma_f32_16x16x32_bf16 v[26:29], v[144:147], v[204:207], 0
	v_mfma_f32_16x16x32_bf16 v[14:17], v[136:139], v[212:215], 0
	v_mfma_f32_16x16x32_bf16 v[10:13], v[144:147], v[212:215], 0
	v_mfma_f32_16x16x32_bf16 v[62:65], v[140:143], v[172:175], v[62:65]
	v_mfma_f32_16x16x32_bf16 v[58:61], v[148:151], v[172:175], v[58:61]
	v_mfma_f32_16x16x32_bf16 v[46:49], v[140:143], v[200:203], v[46:49]
	v_mfma_f32_16x16x32_bf16 v[42:45], v[148:151], v[200:203], v[42:45]
	v_mfma_f32_16x16x32_bf16 v[30:33], v[140:143], v[208:211], v[30:33]
	v_mfma_f32_16x16x32_bf16 v[26:29], v[148:151], v[208:211], v[26:29]
	v_mfma_f32_16x16x32_bf16 v[14:17], v[140:143], v[234:237], v[14:17]
	v_mfma_f32_16x16x32_bf16 v[10:13], v[148:151], v[234:237], v[10:13]
	s_setprio 0
	s_setprio 1
	v_mfma_f32_16x16x32_bf16 v[54:57], v[152:155], v[168:171], 0
	v_mfma_f32_16x16x32_bf16 v[50:53], v[160:163], v[168:171], 0
	v_mfma_f32_16x16x32_bf16 v[38:41], v[152:155], v[196:199], 0
	v_mfma_f32_16x16x32_bf16 v[34:37], v[160:163], v[196:199], 0
	v_mfma_f32_16x16x32_bf16 v[22:25], v[152:155], v[204:207], 0
	v_mfma_f32_16x16x32_bf16 v[18:21], v[160:163], v[204:207], 0
	v_mfma_f32_16x16x32_bf16 v[6:9], v[152:155], v[212:215], 0
	v_mfma_f32_16x16x32_bf16 v[2:5], v[160:163], v[212:215], 0
	v_mfma_f32_16x16x32_bf16 v[54:57], v[156:159], v[172:175], v[54:57]
	v_mfma_f32_16x16x32_bf16 v[50:53], v[164:167], v[172:175], v[50:53]
	v_mfma_f32_16x16x32_bf16 v[38:41], v[156:159], v[200:203], v[38:41]
	v_mfma_f32_16x16x32_bf16 v[34:37], v[164:167], v[200:203], v[34:37]
	v_mfma_f32_16x16x32_bf16 v[22:25], v[156:159], v[208:211], v[22:25]
	v_mfma_f32_16x16x32_bf16 v[18:21], v[164:167], v[208:211], v[18:21]
	v_mfma_f32_16x16x32_bf16 v[6:9], v[156:159], v[234:237], v[6:9]
	v_mfma_f32_16x16x32_bf16 v[2:5], v[164:167], v[234:237], v[2:5]
	s_setprio 0
	s_barrier
	s_add_i32 s58, 0, 0x18000
	s_add_i32 s59, 0, 0x1c000
	v_add_u32_e32 v148, s58, v179
	v_add_u32_e32 v164, s59, v179
	ds_read_b128 v[136:139], v148
	ds_read_b128 v[140:143], v148 offset:1024
	ds_read_b128 v[144:147], v148 offset:2048
	ds_read_b128 v[148:151], v148 offset:3072
	ds_read_b128 v[152:155], v164
	ds_read_b128 v[156:159], v164 offset:1024
	ds_read_b128 v[160:163], v164 offset:2048
	ds_read_b128 v[164:167], v164 offset:3072
	s_add_u32 s16, s22, 0x160000
	s_addc_u32 s17, s23, 0
	s_mov_b32 m0, s29
	v_lshl_add_u64 v[242:243], s[16:17], 0, v[0:1]
	ds_read_b128 v[168:171], v194 offset:32768
	ds_read_b128 v[172:175], v194 offset:33792
	ds_read_b128 v[196:199], v194 offset:34816
	ds_read_b128 v[200:203], v194 offset:35840
	ds_read_b128 v[204:207], v194 offset:36864
	ds_read_b128 v[208:211], v194 offset:37888
	ds_read_b128 v[212:215], v194 offset:38912
	ds_read_b128 v[234:237], v194 offset:39936
	global_load_lds_dwordx4 v[242:243], off
	v_lshl_add_u64 v[242:243], s[16:17], 0, v[130:131]
	s_mov_b32 m0, s30
	s_nop 0
	global_load_lds_dwordx4 v[242:243], off
	s_waitcnt vmcnt(8)
	s_waitcnt lgkmcnt(0)
	s_barrier
	s_setprio 1
	s_waitcnt lgkmcnt(0)
	v_mfma_f32_16x16x32_bf16 v[126:129], v[136:139], v[168:171], v[126:129]
	v_mfma_f32_16x16x32_bf16 v[122:125], v[144:147], v[168:171], v[122:125]
	v_mfma_f32_16x16x32_bf16 v[110:113], v[136:139], v[196:199], v[110:113]
	v_mfma_f32_16x16x32_bf16 v[106:109], v[144:147], v[196:199], v[106:109]
	v_mfma_f32_16x16x32_bf16 v[94:97], v[136:139], v[204:207], v[94:97]
	v_mfma_f32_16x16x32_bf16 v[90:93], v[144:147], v[204:207], v[90:93]
	v_mfma_f32_16x16x32_bf16 v[78:81], v[136:139], v[212:215], v[78:81]
	v_mfma_f32_16x16x32_bf16 v[74:77], v[144:147], v[212:215], v[74:77]
	v_mfma_f32_16x16x32_bf16 v[126:129], v[140:143], v[172:175], v[126:129]
	v_mfma_f32_16x16x32_bf16 v[122:125], v[148:151], v[172:175], v[122:125]
	v_mfma_f32_16x16x32_bf16 v[110:113], v[140:143], v[200:203], v[110:113]
	v_mfma_f32_16x16x32_bf16 v[106:109], v[148:151], v[200:203], v[106:109]
	v_mfma_f32_16x16x32_bf16 v[94:97], v[140:143], v[208:211], v[94:97]
	v_mfma_f32_16x16x32_bf16 v[90:93], v[148:151], v[208:211], v[90:93]
	v_mfma_f32_16x16x32_bf16 v[78:81], v[140:143], v[234:237], v[78:81]
	v_mfma_f32_16x16x32_bf16 v[74:77], v[148:151], v[234:237], v[74:77]
	s_setprio 0
	s_setprio 1
	v_mfma_f32_16x16x32_bf16 v[118:121], v[152:155], v[168:171], v[118:121]
	v_mfma_f32_16x16x32_bf16 v[114:117], v[160:163], v[168:171], v[114:117]
	v_mfma_f32_16x16x32_bf16 v[102:105], v[152:155], v[196:199], v[102:105]
	v_mfma_f32_16x16x32_bf16 v[98:101], v[160:163], v[196:199], v[98:101]
	v_mfma_f32_16x16x32_bf16 v[86:89], v[152:155], v[204:207], v[86:89]
	v_mfma_f32_16x16x32_bf16 v[82:85], v[160:163], v[204:207], v[82:85]
	v_mfma_f32_16x16x32_bf16 v[70:73], v[152:155], v[212:215], v[70:73]
	v_mfma_f32_16x16x32_bf16 v[66:69], v[160:163], v[212:215], v[66:69]
	v_mfma_f32_16x16x32_bf16 v[118:121], v[156:159], v[172:175], v[118:121]
	v_mfma_f32_16x16x32_bf16 v[114:117], v[164:167], v[172:175], v[114:117]
	v_mfma_f32_16x16x32_bf16 v[102:105], v[156:159], v[200:203], v[102:105]
	v_mfma_f32_16x16x32_bf16 v[98:101], v[164:167], v[200:203], v[98:101]
	v_mfma_f32_16x16x32_bf16 v[86:89], v[156:159], v[208:211], v[86:89]
	v_mfma_f32_16x16x32_bf16 v[82:85], v[164:167], v[208:211], v[82:85]
	v_mfma_f32_16x16x32_bf16 v[70:73], v[156:159], v[234:237], v[70:73]
	v_mfma_f32_16x16x32_bf16 v[66:69], v[164:167], v[234:237], v[66:69]
	s_setprio 0
	s_barrier
; #define PG8_STAGE(bufoff, gbase, voff) do { _Pragma("unroll") for (int _i = 0; _i < 2; ++_i) \
;         __builtin_amdgcn_global_load_lds((const unsigned*)((const char*)(gbase) + (voff)[_i]), (LAS unsigned*)(lds + (bufoff) + ldsw + _i * 8192), 16, 0, 0); } while (0)
; #define PG8_LDA(dst, b, h) do { _Pragma("unroll") for (int m = 0; m < 4; ++m) _Pragma("unroll") for (int k = 0; k < 2; ++k) dst[m][k] = *(const LAS bf16x8*)(lds + PG8_SA(b, h) + aoff + m * 2048 + k * 1024); } while (0)
; #define PG8_MMA(ai, bj, At, Bt) do { __builtin_amdgcn_s_setprio(1); _Pragma("unroll") for (int m = 0; m < 4; ++m) _Pragma("unroll") for (int n = 0; n < 2; ++n) _Pragma("unroll") for (int k = 0; k < 2; ++k) \
;         acc[ai][bj][m][n] = __builtin_amdgcn_mfma_f32_16x16x32_bf16(Bt[n][k], At[m][k], acc[ai][bj][m][n], 0, 0, 0); __builtin_amdgcn_s_setprio(0); } while (0)
; #define PG8_WAIT_V(n) asm volatile("s_waitcnt vmcnt(" #n ")" ::: "memory")
; #define PG8_WAIT_L(n) asm volatile("s_waitcnt lgkmcnt(" #n ")" ::: "memory")
; #define PG8_BAR __builtin_amdgcn_s_barrier()
; #define PG8_SCHED __builtin_amdgcn_sched_barrier(0)
; template <class Epi, class Sched, bool ALIGN_EPI = true, bool SP2 = true>
; __device__ __forceinline__ void gemm_phase(LAS unsigned char* lds, const Gemm g, const Sched& S, const Epi& E) {
;     ...
;             PG8_LDA(At, 1, 1); PG8_STAGE(PG8_SB(1, 0), b3, voffB); PG8_STAGE(PG8_SB(1, 1), b3 + hstep, voffB); PG8_STAGE(PG8_SA(1, 0), a3, voffA);
;             PG8_WAIT_V(8); PG8_WAIT_L(0); PG8_BAR; PG8_MMA(1, 0, At, B0); PG8_MMA(1, 1, At, B1); PG8_BAR; PG8_SCHED;
	s_add_i32 s16, s58, s26
	v_lshl_add_u64 v[176:177], v[176:177], 0, s[92:93]
	s_mov_b32 m0, s16
	ds_read_b128 v[168:171], v194 offset:49152
	ds_read_b128 v[172:175], v194 offset:50176
	ds_read_b128 v[196:199], v194 offset:51200
	ds_read_b128 v[200:203], v194 offset:52224
	ds_read_b128 v[204:207], v194 offset:53248
	ds_read_b128 v[208:211], v194 offset:54272
	ds_read_b128 v[212:215], v194 offset:55296
	ds_read_b128 v[234:237], v194 offset:56320
	global_load_lds_dwordx4 v[176:177], off
	s_add_i32 m0, s16, 0x2000
	s_add_u32 s16, s20, 0x160080
	v_lshl_add_u64 v[176:177], v[224:225], 0, s[92:93]
	s_addc_u32 s17, s21, 0
	s_add_i32 s20, s59, s26
	global_load_lds_dwordx4 v[176:177], off
	v_lshl_add_u64 v[176:177], s[16:17], 0, v[0:1]
	s_mov_b32 m0, s20
	s_nop 0
	global_load_lds_dwordx4 v[176:177], off
	v_lshl_add_u64 v[176:177], s[16:17], 0, v[130:131]
	s_add_i32 m0, s20, 0x2000
	s_nop 0
	global_load_lds_dwordx4 v[176:177], off
	v_lshl_add_u64 v[176:177], v[238:239], 0, s[92:93]
	s_mov_b32 m0, s31
	s_nop 0
	global_load_lds_dwordx4 v[176:177], off
	v_lshl_add_u64 v[176:177], v[240:241], 0, s[92:93]
	s_mov_b32 m0, s34
	s_nop 0
	global_load_lds_dwordx4 v[176:177], off
	s_waitcnt vmcnt(8)
	s_waitcnt lgkmcnt(0)
	s_barrier
	s_setprio 1
	s_waitcnt lgkmcnt(0)
	v_mfma_f32_16x16x32_bf16 v[62:65], v[136:139], v[168:171], v[62:65]
	v_mfma_f32_16x16x32_bf16 v[58:61], v[144:147], v[168:171], v[58:61]
	v_mfma_f32_16x16x32_bf16 v[46:49], v[136:139], v[196:199], v[46:49]
	v_mfma_f32_16x16x32_bf16 v[42:45], v[144:147], v[196:199], v[42:45]
	v_mfma_f32_16x16x32_bf16 v[30:33], v[136:139], v[204:207], v[30:33]
	v_mfma_f32_16x16x32_bf16 v[26:29], v[144:147], v[204:207], v[26:29]
	v_mfma_f32_16x16x32_bf16 v[14:17], v[136:139], v[212:215], v[14:17]
	v_mfma_f32_16x16x32_bf16 v[10:13], v[144:147], v[212:215], v[10:13]
	v_mfma_f32_16x16x32_bf16 v[62:65], v[140:143], v[172:175], v[62:65]
	v_mfma_f32_16x16x32_bf16 v[58:61], v[148:151], v[172:175], v[58:61]
	v_mfma_f32_16x16x32_bf16 v[46:49], v[140:143], v[200:203], v[46:49]
	v_mfma_f32_16x16x32_bf16 v[42:45], v[148:151], v[200:203], v[42:45]
	v_mfma_f32_16x16x32_bf16 v[30:33], v[140:143], v[208:211], v[30:33]
	v_mfma_f32_16x16x32_bf16 v[26:29], v[148:151], v[208:211], v[26:29]
	v_mfma_f32_16x16x32_bf16 v[14:17], v[140:143], v[234:237], v[14:17]
	v_mfma_f32_16x16x32_bf16 v[10:13], v[148:151], v[234:237], v[10:13]
	s_setprio 0
	s_setprio 1
	v_mfma_f32_16x16x32_bf16 v[54:57], v[152:155], v[168:171], v[54:57]
	v_mfma_f32_16x16x32_bf16 v[50:53], v[160:163], v[168:171], v[50:53]
	v_mfma_f32_16x16x32_bf16 v[38:41], v[152:155], v[196:199], v[38:41]
	v_mfma_f32_16x16x32_bf16 v[34:37], v[160:163], v[196:199], v[34:37]
	v_mfma_f32_16x16x32_bf16 v[22:25], v[152:155], v[204:207], v[22:25]
	v_mfma_f32_16x16x32_bf16 v[18:21], v[160:163], v[204:207], v[18:21]
	v_mfma_f32_16x16x32_bf16 v[6:9], v[152:155], v[212:215], v[6:9]
	v_mfma_f32_16x16x32_bf16 v[2:5], v[160:163], v[212:215], v[2:5]
	v_mfma_f32_16x16x32_bf16 v[54:57], v[156:159], v[172:175], v[54:57]
	v_mfma_f32_16x16x32_bf16 v[50:53], v[164:167], v[172:175], v[50:53]
	v_mfma_f32_16x16x32_bf16 v[38:41], v[156:159], v[200:203], v[38:41]
	v_mfma_f32_16x16x32_bf16 v[34:37], v[164:167], v[200:203], v[34:37]
	v_mfma_f32_16x16x32_bf16 v[22:25], v[156:159], v[208:211], v[22:25]
	v_mfma_f32_16x16x32_bf16 v[18:21], v[164:167], v[208:211], v[18:21]
	v_mfma_f32_16x16x32_bf16 v[6:9], v[156:159], v[234:237], v[6:9]
	v_mfma_f32_16x16x32_bf16 v[2:5], v[164:167], v[234:237], v[2:5]
	s_setprio 0
	s_barrier
	s_add_i32 s74, s74, 2
	s_add_u32 s72, s72, 0x100
	s_addc_u32 s73, s73, 0
	s_cmpk_gt_u32 s74, 0x55
	s_mov_b64 s[16:17], s[18:19]
